# v17 + out-proj GEMMs start accumulators from the residual (loads issued at the unit header into acc registers, epilogue loses its load/wait/add rounds)
# baseline (speedup 1.0000x reference)
.LBB0_518:
	s_ashr_i32 s19, s18, 31
	s_lshl_b64 s[34:35], s[18:19], 20
	s_add_u32 s34, s56, s34
	s_addc_u32 s35, s57, s35
	s_and_b64 s[6:7], s[6:7], exec
	s_cselect_b32 s19, s35, s41
	s_cselect_b32 s73, s34, s40
	s_add_u32 s74, s40, 0x100
	s_addc_u32 s75, s41, 0
	s_mov_b32 s76, -2
	s_waitcnt lgkmcnt(0)
	v_readlane_b32 s98, v248, 9
	v_readlane_b32 s99, v248, 10
	v_lshl_add_u32 v249, s71, 8, v174
	v_lshl_or_b32 v250, s72, 8, v176
	v_lshlrev_b32_e32 v249, 13, v249
	v_lshl_add_u32 v249, v250, 2, v249
	s_nop 1
	global_load_dwordx4 v[124:127], v249, s[98:99]
	global_load_dwordx4 v[120:123], v249, s[98:99] offset:64
	global_load_dwordx4 v[112:115], v249, s[98:99] offset:512
	global_load_dwordx4 v[108:111], v249, s[98:99] offset:576
	v_add_u32_e32 v249, 0x20000, v249
	global_load_dwordx4 v[116:119], v249, s[98:99]
	global_load_dwordx4 v[104:107], v249, s[98:99] offset:64
	global_load_dwordx4 v[100:103], v249, s[98:99] offset:512
	global_load_dwordx4 v[96:99], v249, s[98:99] offset:576
	v_add_u32_e32 v249, 0x20000, v249
	global_load_dwordx4 v[92:95], v249, s[98:99]
	global_load_dwordx4 v[88:91], v249, s[98:99] offset:64
	global_load_dwordx4 v[84:87], v249, s[98:99] offset:512
	global_load_dwordx4 v[80:83], v249, s[98:99] offset:576
	v_add_u32_e32 v249, 0x20000, v249
	global_load_dwordx4 v[76:79], v249, s[98:99]
	global_load_dwordx4 v[72:75], v249, s[98:99] offset:64
	global_load_dwordx4 v[68:71], v249, s[98:99] offset:512
	global_load_dwordx4 v[64:67], v249, s[98:99] offset:576
	v_add_u32_e32 v249, 0xa0000, v249
	global_load_dwordx4 v[60:63], v249, s[98:99]
	global_load_dwordx4 v[56:59], v249, s[98:99] offset:64
	global_load_dwordx4 v[48:51], v249, s[98:99] offset:512
	global_load_dwordx4 v[44:47], v249, s[98:99] offset:576
	v_add_u32_e32 v249, 0x20000, v249
	global_load_dwordx4 v[52:55], v249, s[98:99]
	global_load_dwordx4 v[40:43], v249, s[98:99] offset:64
	global_load_dwordx4 v[36:39], v249, s[98:99] offset:512
	global_load_dwordx4 v[32:35], v249, s[98:99] offset:576
	v_add_u32_e32 v249, 0x20000, v249
	global_load_dwordx4 v[28:31], v249, s[98:99]
	global_load_dwordx4 v[24:27], v249, s[98:99] offset:64
	global_load_dwordx4 v[20:23], v249, s[98:99] offset:512
	global_load_dwordx4 v[16:19], v249, s[98:99] offset:576
	v_add_u32_e32 v249, 0x20000, v249
	global_load_dwordx4 v[12:15], v249, s[98:99]
	global_load_dwordx4 v[8:11], v249, s[98:99] offset:64
	global_load_dwordx4 v[4:7], v249, s[98:99] offset:512
	global_load_dwordx4 v[0:3], v249, s[98:99] offset:576

.LBB0_522:
	v_lshl_add_u32 v168, s71, 8, v174
	v_lshl_or_b32 v164, s72, 8, v176
	v_readlane_b32 s72, v248, 9
	v_ashrrev_i32_e32 v165, 31, v164
	v_ashrrev_i32_e32 v169, 31, v168
	v_readlane_b32 s73, v248, 10
	v_lshlrev_b64 v[128:129], 13, v[168:169]
	v_readlane_b32 s74, v248, 11
	v_lshl_add_u64 v[166:167], v[164:165], 2, s[72:73]
	v_lshl_add_u64 v[128:129], v[166:167], 0, v[128:129]
	s_nop 0
	s_nop 0
	s_nop 0
	s_nop 0
	v_or_b32_e32 v128, 16, v168
	v_ashrrev_i32_e32 v129, 31, v128
	v_lshlrev_b64 v[130:131], 13, v[128:129]
	v_lshl_add_u64 v[130:131], v[166:167], 0, v[130:131]
	s_nop 0
	s_nop 0
	v_readlane_b32 s75, v248, 12
	v_readlane_b32 s76, v248, 13
	v_readlane_b32 s77, v248, 14
	v_readlane_b32 s78, v248, 15
	v_readlane_b32 s79, v248, 16
	v_or_b32_e32 v172, 32, v168
	v_readlane_b32 s72, v248, 0
	v_or_b32_e32 v170, 48, v168
	v_ashrrev_i32_e32 v173, 31, v172
	v_readlane_b32 s76, v248, 4
	v_readlane_b32 s77, v248, 5
	v_ashrrev_i32_e32 v171, 31, v170
	v_lshlrev_b64 v[132:133], 11, v[168:169]
	v_lshlrev_b64 v[134:135], 13, v[172:173]
	v_readlane_b32 s78, v248, 6
	v_readlane_b32 s79, v248, 7
	s_mov_b64 s[24:25], s[76:77]
	v_lshlrev_b64 v[136:137], 13, v[170:171]
	v_lshl_add_u64 v[132:133], v[132:133], 0, v[164:165]
	v_lshlrev_b64 v[128:129], 11, v[128:129]
	v_lshl_add_u64 v[134:135], v[166:167], 0, v[134:135]
	s_mov_b64 s[26:27], s[78:79]
	v_lshl_add_u64 v[226:227], v[166:167], 0, v[136:137]
	v_lshl_add_u64 v[228:229], v[132:133], 2, s[26:27]
	v_lshl_add_u64 v[230:231], v[132:133], 1, s[10:11]
	v_lshl_add_u64 v[232:233], v[128:129], 0, v[164:165]
	s_nop 0
	s_nop 0
	s_nop 0
	s_nop 0
	s_nop 0
	s_nop 0
	s_nop 0
	s_nop 0
	s_nop 0
	s_nop 0
	s_nop 0
	v_lshl_add_u64 v[226:227], v[232:233], 2, s[26:27]
	v_readlane_b32 s80, v248, 17
	v_readlane_b32 s81, v248, 18
	v_readlane_b32 s82, v248, 19
	v_readlane_b32 s83, v248, 20
	v_readlane_b32 s84, v248, 21
	v_readlane_b32 s85, v248, 22
	v_readlane_b32 s86, v248, 23
	v_readlane_b32 s87, v248, 24
	v_readlane_b32 s73, v248, 1
	v_readlane_b32 s74, v248, 2
	v_readlane_b32 s75, v248, 3
	s_nop 0
	s_nop 0
	s_nop 0
	s_nop 0
	s_nop 0
	s_nop 0
	global_store_dwordx4 v[228:229], v[124:127], off
	v_mul_f32_e32 v182, v125, v125
	v_cvt_pk_bf16_f32 v180, v124, v125
	v_cvt_pk_bf16_f32 v181, v126, v127
	s_nop 0
	v_mul_f32_e32 v125, v121, v121
	s_nop 0
	v_mul_f32_e32 v183, v127, v127
	v_mul_f32_e32 v127, v123, v123
	v_mul_f32_e32 v184, v113, v113
	global_store_dwordx2 v[230:231], v[180:181], off
	global_store_dwordx4 v[228:229], v[120:123], off offset:64
	v_fmac_f32_e32 v125, v120, v120
	s_nop 0
	v_cvt_pk_bf16_f32 v120, v120, v121
	v_cvt_pk_bf16_f32 v121, v122, v123
	v_mul_f32_e32 v185, v115, v115
	v_mul_f32_e32 v186, v109, v109
	v_fmac_f32_e32 v182, v124, v124
	v_fmac_f32_e32 v183, v126, v126
	v_fmac_f32_e32 v127, v122, v122
	v_fmac_f32_e32 v184, v112, v112
	global_store_dwordx2 v[230:231], v[120:121], off offset:32
	global_store_dwordx4 v[228:229], v[112:115], off offset:512
	v_mul_f32_e32 v187, v111, v111
	s_nop 0
	v_cvt_pk_bf16_f32 v112, v112, v113
	v_cvt_pk_bf16_f32 v113, v114, v115
	s_nop 0
	v_fmac_f32_e32 v185, v114, v114
	v_fmac_f32_e32 v186, v108, v108
	v_add_f32_e32 v122, v182, v183
	v_add_f32_e32 v123, v125, v127
	global_store_dwordx2 v[230:231], v[112:113], off offset:256
	global_store_dwordx4 v[228:229], v[108:111], off offset:576
	v_fmac_f32_e32 v187, v110, v110
	v_add_f32_e32 v120, v184, v185
	v_cvt_pk_bf16_f32 v108, v108, v109
	v_cvt_pk_bf16_f32 v109, v110, v111
	v_add_f32_e32 v115, v122, v123
	global_store_dwordx2 v[230:231], v[108:109], off offset:288
	v_mul_f32_e32 v108, v117, v117
	v_mul_f32_e32 v109, v119, v119
	v_add_f32_e32 v114, v186, v187
	v_add_f32_e32 v110, v115, v120
	v_fmac_f32_e32 v108, v116, v116
	v_fmac_f32_e32 v109, v118, v118
	v_add_f32_e32 v112, v110, v114
	global_store_dwordx4 v[226:227], v[116:119], off
	v_add_f32_e32 v113, v108, v109
	v_cvt_pk_bf16_f32 v108, v116, v117
	v_lshl_add_u64 v[110:111], v[232:233], 1, s[10:11]
	s_nop 0
	v_cvt_pk_bf16_f32 v109, v118, v119
	global_store_dwordx2 v[110:111], v[108:109], off
	s_nop 0
	v_mul_f32_e32 v108, v105, v105
	global_store_dwordx4 v[226:227], v[104:107], off offset:64
	v_fmac_f32_e32 v108, v104, v104
	s_nop 0
	v_cvt_pk_bf16_f32 v104, v104, v105
	v_cvt_pk_bf16_f32 v105, v106, v107
	global_store_dwordx2 v[110:111], v[104:105], off offset:32
	s_nop 0
	v_mul_f32_e32 v104, v101, v101
	global_store_dwordx4 v[226:227], v[100:103], off offset:512
	v_fmac_f32_e32 v104, v100, v100
	s_nop 0
	v_cvt_pk_bf16_f32 v100, v100, v101
	v_cvt_pk_bf16_f32 v101, v102, v103
	global_store_dwordx2 v[110:111], v[100:101], off offset:256
	s_nop 0
	v_mul_f32_e32 v100, v97, v97
	global_store_dwordx4 v[226:227], v[96:99], off offset:576
	v_fmac_f32_e32 v100, v96, v96
	v_mul_f32_e32 v101, v99, v99
	v_cvt_pk_bf16_f32 v96, v96, v97
	v_cvt_pk_bf16_f32 v97, v98, v99
	global_store_dwordx2 v[110:111], v[96:97], off offset:288
	v_lshlrev_b64 v[96:97], 11, v[172:173]
	v_mul_f32_e32 v105, v103, v103
	v_fmac_f32_e32 v101, v98, v98
	v_lshl_add_u64 v[96:97], v[96:97], 0, v[164:165]
	s_nop 0
	s_nop 0
	v_fmac_f32_e32 v105, v102, v102
	v_add_f32_e32 v100, v100, v101
	v_lshl_add_u64 v[98:99], v[96:97], 2, s[26:27]
	v_mul_f32_e32 v101, v93, v93
	v_mul_f32_e32 v102, v95, v95
	global_store_dwordx4 v[98:99], v[92:95], off
	v_fmac_f32_e32 v101, v92, v92
	v_fmac_f32_e32 v102, v94, v94
	v_cvt_pk_bf16_f32 v92, v92, v93
	v_cvt_pk_bf16_f32 v93, v94, v95
	v_lshl_add_u64 v[94:95], v[96:97], 1, s[10:11]
	s_nop 0
	global_store_dwordx2 v[94:95], v[92:93], off
	s_nop 0
	v_mul_f32_e32 v92, v89, v89
	global_store_dwordx4 v[98:99], v[88:91], off offset:64
	v_fmac_f32_e32 v92, v88, v88
	s_nop 0
	v_cvt_pk_bf16_f32 v88, v88, v89
	v_cvt_pk_bf16_f32 v89, v90, v91
	global_store_dwordx2 v[94:95], v[88:89], off offset:32
	s_nop 0
	v_mul_f32_e32 v88, v85, v85
	global_store_dwordx4 v[98:99], v[84:87], off offset:512
	v_fmac_f32_e32 v88, v84, v84
	s_nop 0
	v_cvt_pk_bf16_f32 v84, v84, v85
	v_cvt_pk_bf16_f32 v85, v86, v87
	global_store_dwordx2 v[94:95], v[84:85], off offset:256
	s_nop 0
	v_mul_f32_e32 v84, v81, v81
	global_store_dwordx4 v[98:99], v[80:83], off offset:576
	v_fmac_f32_e32 v84, v80, v80
	v_mul_f32_e32 v85, v83, v83
	v_cvt_pk_bf16_f32 v80, v80, v81
	v_cvt_pk_bf16_f32 v81, v82, v83
	global_store_dwordx2 v[94:95], v[80:81], off offset:288
	v_lshlrev_b64 v[80:81], 11, v[170:171]
	v_mul_f32_e32 v89, v87, v87
	v_fmac_f32_e32 v85, v82, v82
	v_lshl_add_u64 v[80:81], v[80:81], 0, v[164:165]
	s_nop 0
	s_nop 0
	v_fmac_f32_e32 v89, v86, v86
	v_add_f32_e32 v84, v84, v85
	v_lshl_add_u64 v[82:83], v[80:81], 2, s[26:27]
	v_mul_f32_e32 v85, v77, v77
	v_mul_f32_e32 v86, v79, v79
	global_store_dwordx4 v[82:83], v[76:79], off
	v_fmac_f32_e32 v85, v76, v76
	v_fmac_f32_e32 v86, v78, v78
	v_cvt_pk_bf16_f32 v76, v76, v77
	v_cvt_pk_bf16_f32 v77, v78, v79
	v_lshl_add_u64 v[78:79], v[80:81], 1, s[10:11]
	s_nop 0
	global_store_dwordx2 v[78:79], v[76:77], off
	s_nop 0
	v_mul_f32_e32 v76, v73, v73
	global_store_dwordx4 v[82:83], v[72:75], off offset:64
	v_fmac_f32_e32 v76, v72, v72
	v_mul_f32_e32 v77, v75, v75
	v_cvt_pk_bf16_f32 v72, v72, v73
	v_cvt_pk_bf16_f32 v73, v74, v75
	s_nop 0
	s_nop 0
	v_fmac_f32_e32 v77, v74, v74
	global_store_dwordx2 v[78:79], v[72:73], off offset:32
	v_mul_f32_e32 v72, v69, v69
	v_mul_f32_e32 v73, v71, v71
	v_add_f32_e32 v85, v85, v86
	v_add_f32_e32 v76, v76, v77
	v_fmac_f32_e32 v72, v68, v68
	v_fmac_f32_e32 v73, v70, v70
	v_add_f32_e32 v76, v85, v76
	v_add_f32_e32 v72, v72, v73
	v_add_f32_e32 v76, v76, v72
	v_mov_b64_e32 v[74:75], v[66:67]
	v_mov_b64_e32 v[72:73], v[64:65]
	v_mul_f32_e32 v65, v75, v75
	v_mul_f32_e32 v64, v73, v73
	v_fmac_f32_e32 v64, v72, v72
	v_fmac_f32_e32 v65, v74, v74
	global_store_dwordx4 v[82:83], v[68:71], off offset:512
	v_add_f32_e32 v64, v64, v65
	v_and_b32_e32 v65, 64, v179
	v_cvt_pk_bf16_f32 v68, v68, v69
	v_cvt_pk_bf16_f32 v69, v70, v71
	global_store_dwordx2 v[78:79], v[68:69], off offset:256
	v_add_f32_e32 v67, v76, v64
	v_xor_b32_e32 v64, 16, v179
	v_add_u32_e32 v68, 64, v65
	v_mul_f32_e32 v109, v107, v107
	v_mul_f32_e32 v93, v91, v91
	v_cmp_lt_i32_e32 vcc, v64, v68
	v_fmac_f32_e32 v109, v106, v106
	v_fmac_f32_e32 v93, v90, v90
	v_cndmask_b32_e32 v64, v179, v64, vcc
	v_add_f32_e32 v108, v108, v109
	v_add_f32_e32 v101, v101, v102
	v_add_f32_e32 v92, v92, v93
	v_lshlrev_b32_e32 v90, 2, v64
	v_add_f32_e32 v108, v113, v108
	v_add_f32_e32 v104, v104, v105
	v_add_f32_e32 v92, v101, v92
	v_add_f32_e32 v88, v88, v89
	ds_bpermute_b32 v69, v90, v67
	v_add_f32_e32 v104, v108, v104
	v_add_f32_e32 v88, v92, v88
	v_add_f32_e32 v100, v104, v100
	v_add_f32_e32 v84, v88, v84
	ds_bpermute_b32 v64, v90, v112
	ds_bpermute_b32 v65, v90, v100
	ds_bpermute_b32 v66, v90, v84
	s_waitcnt lgkmcnt(3)
	v_add_f32_e32 v67, v67, v69
	v_xor_b32_e32 v69, 32, v179
	v_cmp_lt_i32_e32 vcc, v69, v68
	s_waitcnt lgkmcnt(2)
	v_add_f32_e32 v64, v112, v64
	s_waitcnt lgkmcnt(1)
	v_add_f32_e32 v65, v100, v65
	v_cndmask_b32_e32 v68, v179, v69, vcc
	s_waitcnt lgkmcnt(0)
	v_add_f32_e32 v66, v84, v66
	v_lshlrev_b32_e32 v91, 2, v68
	ds_bpermute_b32 v68, v91, v64
	ds_bpermute_b32 v69, v91, v65
	ds_bpermute_b32 v70, v91, v66
	ds_bpermute_b32 v71, v91, v67
	v_lshl_add_u64 v[84:85], v[168:169], 2, s[12:13]
	global_store_dwordx4 v[82:83], v[72:75], off offset:576
	s_nop 1
	v_cvt_pk_bf16_f32 v72, v72, v73
	v_cvt_pk_bf16_f32 v73, v74, v75
	global_store_dwordx2 v[78:79], v[72:73], off offset:288
	s_and_saveexec_b64 s[6:7], s[2:3]
	s_cbranch_execz .LBB0_524
	s_waitcnt lgkmcnt(3)
	v_add_f32_e32 v64, v64, v68
	s_waitcnt lgkmcnt(0)
	v_add_f32_e32 v67, v67, v71
	v_add_f32_e32 v66, v66, v70
	v_add_f32_e32 v65, v65, v69
	global_atomic_add_f32 v[84:85], v64, off
	global_atomic_add_f32 v[84:85], v65, off offset:64
	global_atomic_add_f32 v[84:85], v66, off offset:128
	global_atomic_add_f32 v[84:85], v67, off offset:192
.LBB0_524:
	s_or_b64 exec, exec, s[6:7]
	v_add_u32_e32 v64, 0x80, v168
	v_ashrrev_i32_e32 v65, 31, v64
	v_lshlrev_b64 v[66:67], 13, v[64:65]
	v_lshl_add_u64 v[66:67], v[166:167], 0, v[66:67]
	s_nop 0
	s_nop 0
	s_waitcnt lgkmcnt(3)
	v_add_u32_e32 v68, 0x90, v168
	s_waitcnt lgkmcnt(2)
	v_ashrrev_i32_e32 v69, 31, v68
	s_nop 0
	s_nop 0
	s_waitcnt lgkmcnt(0)
	v_lshlrev_b64 v[70:71], 13, v[68:69]
	v_lshl_add_u64 v[66:67], v[166:167], 0, v[70:71]
	s_nop 0
	s_nop 0
	v_add_u32_e32 v88, 0xa0, v168
	v_add_u32_e32 v86, 0xb0, v168
	v_ashrrev_i32_e32 v89, 31, v88
	v_ashrrev_i32_e32 v87, 31, v86
	v_lshlrev_b64 v[70:71], 13, v[88:89]
	v_lshlrev_b64 v[72:73], 13, v[86:87]
	v_lshlrev_b64 v[64:65], 11, v[64:65]
	v_lshlrev_b64 v[68:69], 11, v[68:69]
	v_lshl_add_u64 v[70:71], v[166:167], 0, v[70:71]
	v_lshl_add_u64 v[136:137], v[166:167], 0, v[72:73]
	v_lshl_add_u64 v[138:139], v[64:65], 0, v[164:165]
	v_lshl_add_u64 v[140:141], v[68:69], 0, v[164:165]
	s_nop 0
	s_nop 0
	s_nop 0
	s_nop 0
	s_nop 0
	s_nop 0
	s_nop 0
	s_nop 0
	s_nop 0
	s_nop 0
	s_nop 0
	v_readlane_b32 s72, v248, 0
	v_readlane_b32 s76, v248, 4
	v_readlane_b32 s77, v248, 5
	v_readlane_b32 s78, v248, 6
	v_readlane_b32 s79, v248, 7
	s_mov_b64 s[24:25], s[76:77]
	s_mov_b64 s[26:27], s[78:79]
	v_lshl_add_u64 v[136:137], v[138:139], 2, s[26:27]
	v_lshl_add_u64 v[138:139], v[138:139], 1, s[10:11]
	v_lshl_add_u64 v[142:143], v[140:141], 2, s[26:27]
	v_readlane_b32 s73, v248, 1
	v_readlane_b32 s74, v248, 2
	v_readlane_b32 s75, v248, 3
	s_nop 0
	s_nop 0
	s_nop 0
	s_nop 0
	s_nop 0
	s_nop 0
	s_nop 0
	s_nop 0
	global_store_dwordx4 v[136:137], v[60:63], off
	v_mul_f32_e32 v94, v61, v61
	v_cvt_pk_bf16_f32 v92, v60, v61
	v_cvt_pk_bf16_f32 v93, v62, v63
	s_nop 0
	v_mul_f32_e32 v61, v57, v57
	s_nop 0
	s_nop 0
	v_mul_f32_e32 v95, v63, v63
	v_mul_f32_e32 v63, v59, v59
	v_mul_f32_e32 v96, v49, v49
	global_store_dwordx2 v[138:139], v[92:93], off
	global_store_dwordx4 v[136:137], v[56:59], off offset:64
	v_fmac_f32_e32 v61, v56, v56
	s_nop 0
	v_cvt_pk_bf16_f32 v56, v56, v57
	v_cvt_pk_bf16_f32 v57, v58, v59
	v_mul_f32_e32 v97, v51, v51
	v_mul_f32_e32 v98, v45, v45
	v_fmac_f32_e32 v94, v60, v60
	v_fmac_f32_e32 v95, v62, v62
	v_fmac_f32_e32 v63, v58, v58
	v_fmac_f32_e32 v96, v48, v48
	global_store_dwordx2 v[138:139], v[56:57], off offset:32
	global_store_dwordx4 v[136:137], v[48:51], off offset:512
	s_nop 0
	s_nop 0
	s_nop 0
	v_cvt_pk_bf16_f32 v48, v48, v49
	v_cvt_pk_bf16_f32 v49, v50, v51
	v_mul_f32_e32 v99, v47, v47
	v_fmac_f32_e32 v97, v50, v50
	v_fmac_f32_e32 v98, v44, v44
	v_add_f32_e32 v58, v94, v95
	v_add_f32_e32 v59, v61, v63
	global_store_dwordx2 v[138:139], v[48:49], off offset:256
	global_store_dwordx4 v[136:137], v[44:47], off offset:576
	v_mul_f32_e32 v100, v53, v53
	v_fmac_f32_e32 v99, v46, v46
	v_cvt_pk_bf16_f32 v44, v44, v45
	v_cvt_pk_bf16_f32 v45, v46, v47
	v_add_f32_e32 v56, v96, v97
	v_add_f32_e32 v51, v58, v59
	global_store_dwordx2 v[138:139], v[44:45], off offset:288
	global_store_dwordx4 v[142:143], v[52:55], off
	v_mul_f32_e32 v44, v55, v55
	v_fmac_f32_e32 v100, v52, v52
	v_add_f32_e32 v50, v98, v99
	v_add_f32_e32 v46, v51, v56
	v_fmac_f32_e32 v44, v54, v54
	v_add_f32_e32 v48, v46, v50
	v_add_f32_e32 v49, v100, v44
	v_cvt_pk_bf16_f32 v44, v52, v53
	v_lshl_add_u64 v[46:47], v[140:141], 1, s[10:11]
	s_nop 0
	s_nop 0
	v_cvt_pk_bf16_f32 v45, v54, v55
	global_store_dwordx2 v[46:47], v[44:45], off
	s_nop 0
	v_mul_f32_e32 v44, v41, v41
	global_store_dwordx4 v[142:143], v[40:43], off offset:64
	v_fmac_f32_e32 v44, v40, v40
	s_nop 0
	s_nop 0
	v_cvt_pk_bf16_f32 v40, v40, v41
	v_cvt_pk_bf16_f32 v41, v42, v43
	global_store_dwordx2 v[46:47], v[40:41], off offset:32
	s_nop 0
	v_mul_f32_e32 v40, v37, v37
	global_store_dwordx4 v[142:143], v[36:39], off offset:512
	v_fmac_f32_e32 v40, v36, v36
	s_nop 0
	s_nop 0
	v_cvt_pk_bf16_f32 v36, v36, v37
	v_cvt_pk_bf16_f32 v37, v38, v39
	global_store_dwordx2 v[46:47], v[36:37], off offset:256
	s_nop 0
	v_mul_f32_e32 v36, v33, v33
	global_store_dwordx4 v[142:143], v[32:35], off offset:576
	v_fmac_f32_e32 v36, v32, v32
	v_mul_f32_e32 v37, v35, v35
	v_cvt_pk_bf16_f32 v32, v32, v33
	v_cvt_pk_bf16_f32 v33, v34, v35
	global_store_dwordx2 v[46:47], v[32:33], off offset:288
	v_lshlrev_b64 v[32:33], 11, v[88:89]
	v_mul_f32_e32 v41, v39, v39
	v_fmac_f32_e32 v37, v34, v34
	v_lshl_add_u64 v[32:33], v[32:33], 0, v[164:165]
	s_nop 0
	s_nop 0
	s_nop 0
	v_fmac_f32_e32 v41, v38, v38
	v_add_f32_e32 v36, v36, v37
	v_lshl_add_u64 v[34:35], v[32:33], 2, s[26:27]
	v_mul_f32_e32 v37, v29, v29
	v_mul_f32_e32 v38, v31, v31
	global_store_dwordx4 v[34:35], v[28:31], off
	v_fmac_f32_e32 v37, v28, v28
	v_fmac_f32_e32 v38, v30, v30
	v_cvt_pk_bf16_f32 v28, v28, v29
	v_cvt_pk_bf16_f32 v29, v30, v31
	v_lshl_add_u64 v[30:31], v[32:33], 1, s[10:11]
	s_nop 0
	s_nop 0
	global_store_dwordx2 v[30:31], v[28:29], off
	s_nop 0
	v_mul_f32_e32 v28, v25, v25
	global_store_dwordx4 v[34:35], v[24:27], off offset:64
	v_fmac_f32_e32 v28, v24, v24
	s_nop 0
	s_nop 0
	v_cvt_pk_bf16_f32 v24, v24, v25
	v_cvt_pk_bf16_f32 v25, v26, v27
	global_store_dwordx2 v[30:31], v[24:25], off offset:32
	s_nop 0
	v_mul_f32_e32 v24, v21, v21
	global_store_dwordx4 v[34:35], v[20:23], off offset:512
	v_fmac_f32_e32 v24, v20, v20
	s_nop 0
	s_nop 0
	v_cvt_pk_bf16_f32 v20, v20, v21
	v_cvt_pk_bf16_f32 v21, v22, v23
	global_store_dwordx2 v[30:31], v[20:21], off offset:256
	s_nop 0
	v_mul_f32_e32 v20, v17, v17
	global_store_dwordx4 v[34:35], v[16:19], off offset:576
	v_fmac_f32_e32 v20, v16, v16
	v_mul_f32_e32 v21, v19, v19
	v_cvt_pk_bf16_f32 v16, v16, v17
	v_cvt_pk_bf16_f32 v17, v18, v19
	global_store_dwordx2 v[30:31], v[16:17], off offset:288
	v_lshlrev_b64 v[16:17], 11, v[86:87]
	v_mul_f32_e32 v25, v23, v23
	v_fmac_f32_e32 v21, v18, v18
	v_lshl_add_u64 v[16:17], v[16:17], 0, v[164:165]
	s_nop 0
	s_nop 0
	s_nop 0
	v_fmac_f32_e32 v25, v22, v22
	v_add_f32_e32 v20, v20, v21
	v_lshl_add_u64 v[18:19], v[16:17], 2, s[26:27]
	v_mul_f32_e32 v21, v13, v13
	v_mul_f32_e32 v22, v15, v15
	global_store_dwordx4 v[18:19], v[12:15], off
	v_fmac_f32_e32 v21, v12, v12
	v_fmac_f32_e32 v22, v14, v14
	v_cvt_pk_bf16_f32 v12, v12, v13
	v_cvt_pk_bf16_f32 v13, v14, v15
	v_lshl_add_u64 v[14:15], v[16:17], 1, s[10:11]
	s_nop 0
	s_nop 0
	global_store_dwordx2 v[14:15], v[12:13], off
	s_nop 0
	v_mul_f32_e32 v12, v9, v9
	global_store_dwordx4 v[18:19], v[8:11], off offset:64
	v_fmac_f32_e32 v12, v8, v8
	v_mul_f32_e32 v13, v11, v11
	v_cvt_pk_bf16_f32 v8, v8, v9
	v_cvt_pk_bf16_f32 v9, v10, v11
	s_nop 0
	s_nop 0
	s_nop 0
	v_fmac_f32_e32 v13, v10, v10
	global_store_dwordx2 v[14:15], v[8:9], off offset:32
	v_mul_f32_e32 v8, v5, v5
	v_mul_f32_e32 v9, v7, v7
	v_add_f32_e32 v21, v21, v22
	v_add_f32_e32 v12, v12, v13
	v_fmac_f32_e32 v8, v4, v4
	v_fmac_f32_e32 v9, v6, v6
	v_mul_f32_e32 v45, v43, v43
	v_mul_f32_e32 v29, v27, v27
	v_add_f32_e32 v12, v21, v12
	v_add_f32_e32 v8, v8, v9
	v_fmac_f32_e32 v45, v42, v42
	v_fmac_f32_e32 v29, v26, v26
	v_add_f32_e32 v12, v12, v8
	s_nop 0
	v_mov_b64_e32 v[10:11], v[2:3]
	v_mov_b64_e32 v[8:9], v[0:1]
	v_add_f32_e32 v44, v44, v45
	v_add_f32_e32 v37, v37, v38
	v_add_f32_e32 v28, v28, v29
	v_mul_f32_e32 v0, v9, v9
	v_mul_f32_e32 v1, v11, v11
	v_add_f32_e32 v44, v49, v44
	v_add_f32_e32 v40, v40, v41
	v_add_f32_e32 v28, v37, v28
	v_add_f32_e32 v24, v24, v25
	v_fmac_f32_e32 v0, v8, v8
	v_fmac_f32_e32 v1, v10, v10
	v_add_f32_e32 v40, v44, v40
	v_add_f32_e32 v24, v28, v24
	v_add_f32_e32 v0, v0, v1
	v_add_f32_e32 v36, v40, v36
	v_add_f32_e32 v20, v24, v20
	v_add_f32_e32 v3, v12, v0
	global_store_dwordx4 v[18:19], v[4:7], off offset:512
	ds_bpermute_b32 v0, v90, v48
	ds_bpermute_b32 v1, v90, v36
	v_cvt_pk_bf16_f32 v4, v4, v5
	v_cvt_pk_bf16_f32 v5, v6, v7
	ds_bpermute_b32 v2, v90, v20
	ds_bpermute_b32 v6, v90, v3
	global_store_dwordx2 v[14:15], v[4:5], off offset:256
	s_waitcnt lgkmcnt(3)
	v_add_f32_e32 v0, v48, v0
	s_waitcnt lgkmcnt(2)
	v_add_f32_e32 v1, v36, v1
	s_waitcnt lgkmcnt(1)
	v_add_f32_e32 v2, v20, v2
	s_waitcnt lgkmcnt(0)
	v_add_f32_e32 v4, v3, v6
	ds_bpermute_b32 v3, v91, v0
	ds_bpermute_b32 v5, v91, v1
	ds_bpermute_b32 v6, v91, v2
	ds_bpermute_b32 v7, v91, v4
	global_store_dwordx4 v[18:19], v[8:11], off offset:576
	s_nop 1
	v_cvt_pk_bf16_f32 v8, v8, v9
	v_cvt_pk_bf16_f32 v9, v10, v11
	global_store_dwordx2 v[14:15], v[8:9], off offset:288
	s_and_saveexec_b64 s[6:7], s[2:3]
	s_cbranch_execz .LBB0_526
	s_waitcnt lgkmcnt(3)
	v_add_f32_e32 v0, v0, v3
	s_waitcnt lgkmcnt(0)
	v_add_f32_e32 v4, v4, v7
	v_add_f32_e32 v2, v2, v6
	v_add_f32_e32 v1, v1, v5
	global_atomic_add_f32 v[84:85], v0, off offset:512
	global_atomic_add_f32 v[84:85], v1, off offset:576
	global_atomic_add_f32 v[84:85], v2, off offset:640
	global_atomic_add_f32 v[84:85], v4, off offset:704

.LBB0_991:
	s_ashr_i32 s19, s18, 31
	s_lshl_b64 s[22:23], s[18:19], 22
	s_add_u32 s22, s56, s22
	s_addc_u32 s23, s57, s23
	s_and_b64 s[34:35], s[4:5], exec
	s_cselect_b32 s19, s23, s41
	s_cselect_b32 s71, s22, s40
	s_ashr_i32 s17, s16, 31
	s_lshl_b64 s[34:35], s[16:17], 20
	s_add_u32 s34, s58, s34
	s_addc_u32 s35, s59, s35
	s_and_b64 s[52:53], s[4:5], exec
	s_cselect_b32 s17, s35, s43
	s_cselect_b32 s72, s34, s42
	s_add_u32 s40, s40, 0x200080
	s_addc_u32 s41, s41, 0
	s_add_u32 s73, s42, 0x100
	s_addc_u32 s74, s43, 0
	s_mov_b32 s75, -2
	s_waitcnt lgkmcnt(0)
	s_waitcnt vmcnt(0)
	v_readlane_b32 s98, v248, 6
	v_readlane_b32 s99, v248, 7
	v_lshl_add_u32 v249, s38, 8, v180
	v_lshl_or_b32 v250, s39, 8, v182
	v_lshlrev_b32_e32 v249, 13, v249
	v_lshl_add_u32 v249, v250, 2, v249
	s_nop 1
	global_load_dwordx4 v[124:127], v249, s[98:99]
	global_load_dwordx4 v[120:123], v249, s[98:99] offset:64
	global_load_dwordx4 v[112:115], v249, s[98:99] offset:512
	global_load_dwordx4 v[108:111], v249, s[98:99] offset:576
	v_add_u32_e32 v249, 0x20000, v249
	global_load_dwordx4 v[116:119], v249, s[98:99]
	global_load_dwordx4 v[104:107], v249, s[98:99] offset:64
	global_load_dwordx4 v[100:103], v249, s[98:99] offset:512
	global_load_dwordx4 v[96:99], v249, s[98:99] offset:576
	v_add_u32_e32 v249, 0x20000, v249
	global_load_dwordx4 v[92:95], v249, s[98:99]
	global_load_dwordx4 v[88:91], v249, s[98:99] offset:64
	global_load_dwordx4 v[84:87], v249, s[98:99] offset:512
	global_load_dwordx4 v[80:83], v249, s[98:99] offset:576
	v_add_u32_e32 v249, 0x20000, v249
	global_load_dwordx4 v[76:79], v249, s[98:99]
	global_load_dwordx4 v[72:75], v249, s[98:99] offset:64
	global_load_dwordx4 v[68:71], v249, s[98:99] offset:512
	global_load_dwordx4 v[64:67], v249, s[98:99] offset:576
	v_add_u32_e32 v249, 0xa0000, v249
	global_load_dwordx4 v[60:63], v249, s[98:99]
	global_load_dwordx4 v[56:59], v249, s[98:99] offset:64
	global_load_dwordx4 v[48:51], v249, s[98:99] offset:512
	global_load_dwordx4 v[44:47], v249, s[98:99] offset:576
	v_add_u32_e32 v249, 0x20000, v249
	global_load_dwordx4 v[52:55], v249, s[98:99]
	global_load_dwordx4 v[40:43], v249, s[98:99] offset:64
	global_load_dwordx4 v[36:39], v249, s[98:99] offset:512
	global_load_dwordx4 v[32:35], v249, s[98:99] offset:576
	v_add_u32_e32 v249, 0x20000, v249
	global_load_dwordx4 v[28:31], v249, s[98:99]
	global_load_dwordx4 v[24:27], v249, s[98:99] offset:64
	global_load_dwordx4 v[20:23], v249, s[98:99] offset:512
	global_load_dwordx4 v[16:19], v249, s[98:99] offset:576
	v_add_u32_e32 v249, 0x20000, v249
	global_load_dwordx4 v[12:15], v249, s[98:99]
	global_load_dwordx4 v[8:11], v249, s[98:99] offset:64
	global_load_dwordx4 v[4:7], v249, s[98:99] offset:512
	global_load_dwordx4 v[0:3], v249, s[98:99] offset:576

.LBB0_995:
	v_lshl_add_u32 v168, s38, 8, v180
	v_lshl_or_b32 v164, s39, 8, v182
	v_readlane_b32 s72, v248, 0
	v_ashrrev_i32_e32 v165, 31, v164
	v_ashrrev_i32_e32 v169, 31, v168
	v_readlane_b32 s78, v248, 6
	v_readlane_b32 s79, v248, 7
	v_lshlrev_b64 v[128:129], 13, v[168:169]
	v_or_b32_e32 v174, 32, v168
	v_lshl_add_u64 v[166:167], v[164:165], 2, s[78:79]
	v_lshl_add_u64 v[234:235], v[166:167], 0, v[128:129]
	v_or_b32_e32 v128, 16, v168
	v_ashrrev_i32_e32 v129, 31, v128
	s_nop 0
	s_nop 0
	s_nop 0
	s_nop 0
	v_lshlrev_b64 v[130:131], 13, v[128:129]
	v_lshl_add_u64 v[176:177], v[166:167], 0, v[130:131]
	s_nop 0
	s_nop 0
	v_or_b32_e32 v170, 48, v168
	v_ashrrev_i32_e32 v175, 31, v174
	v_ashrrev_i32_e32 v171, 31, v170
	v_lshlrev_b64 v[130:131], 11, v[168:169]
	v_lshlrev_b64 v[132:133], 13, v[174:175]
	v_lshlrev_b64 v[134:135], 13, v[170:171]
	v_lshl_add_u64 v[130:131], v[130:131], 0, v[164:165]
	v_lshlrev_b64 v[128:129], 11, v[128:129]
	v_lshl_add_u64 v[178:179], v[166:167], 0, v[132:133]
	v_lshl_add_u64 v[172:173], v[166:167], 0, v[134:135]
	v_lshl_add_u64 v[236:237], v[130:131], 1, s[8:9]
	v_lshl_add_u64 v[238:239], v[128:129], 0, v[164:165]
	s_nop 0
	s_nop 0
	s_nop 0
	s_nop 0
	s_nop 0
	s_nop 0
	s_nop 0
	s_nop 0
	s_nop 0
	s_nop 0
	v_readlane_b32 s73, v248, 1
	v_readlane_b32 s74, v248, 2
	v_readlane_b32 s75, v248, 3
	v_readlane_b32 s76, v248, 4
	v_readlane_b32 s77, v248, 5
	s_nop 0
	s_nop 0
	s_nop 0
	s_nop 0
	s_nop 0
	s_nop 0
	global_store_dwordx4 v[234:235], v[124:127], off
	v_mul_f32_e32 v187, v125, v125
	v_cvt_pk_bf16_f32 v188, v124, v125
	v_cvt_pk_bf16_f32 v189, v126, v127
	s_nop 0
	v_mul_f32_e32 v125, v121, v121
	s_nop 0
	v_mul_f32_e32 v190, v127, v127
	v_mul_f32_e32 v127, v123, v123
	v_mul_f32_e32 v191, v113, v113
	global_store_dwordx2 v[236:237], v[188:189], off
	global_store_dwordx4 v[234:235], v[120:123], off offset:64
	v_fmac_f32_e32 v125, v120, v120
	s_nop 0
	v_cvt_pk_bf16_f32 v120, v120, v121
	v_cvt_pk_bf16_f32 v121, v122, v123
	v_mul_f32_e32 v192, v115, v115
	v_mul_f32_e32 v193, v109, v109
	v_fmac_f32_e32 v187, v124, v124
	v_fmac_f32_e32 v190, v126, v126
	v_fmac_f32_e32 v127, v122, v122
	v_fmac_f32_e32 v191, v112, v112
	global_store_dwordx2 v[236:237], v[120:121], off offset:32
	global_store_dwordx4 v[234:235], v[112:115], off offset:512
	v_mul_f32_e32 v194, v111, v111
	s_nop 0
	v_cvt_pk_bf16_f32 v112, v112, v113
	v_cvt_pk_bf16_f32 v113, v114, v115
	s_nop 0
	v_fmac_f32_e32 v192, v114, v114
	v_fmac_f32_e32 v193, v108, v108
	v_add_f32_e32 v123, v187, v190
	v_add_f32_e32 v124, v125, v127
	global_store_dwordx2 v[236:237], v[112:113], off offset:256
	global_store_dwordx4 v[234:235], v[108:111], off offset:576
	v_fmac_f32_e32 v194, v110, v110
	v_mul_f32_e32 v122, v117, v117
	v_cvt_pk_bf16_f32 v108, v108, v109
	v_cvt_pk_bf16_f32 v109, v110, v111
	v_add_f32_e32 v120, v191, v192
	v_add_f32_e32 v115, v123, v124
	global_store_dwordx2 v[236:237], v[108:109], off offset:288
	global_store_dwordx4 v[176:177], v[116:119], off
	v_mul_f32_e32 v108, v119, v119
	v_add_f32_e32 v114, v193, v194
	v_add_f32_e32 v110, v115, v120
	v_fmac_f32_e32 v122, v116, v116
	v_fmac_f32_e32 v108, v118, v118
	v_add_f32_e32 v112, v110, v114
	v_add_f32_e32 v113, v122, v108
	v_cvt_pk_bf16_f32 v108, v116, v117
	v_lshl_add_u64 v[110:111], v[238:239], 1, s[8:9]
	s_nop 0
	v_cvt_pk_bf16_f32 v109, v118, v119
	global_store_dwordx2 v[110:111], v[108:109], off
	s_nop 0
	v_mul_f32_e32 v108, v105, v105
	global_store_dwordx4 v[176:177], v[104:107], off offset:64
	v_fmac_f32_e32 v108, v104, v104
	s_nop 0
	v_cvt_pk_bf16_f32 v104, v104, v105
	v_cvt_pk_bf16_f32 v105, v106, v107
	global_store_dwordx2 v[110:111], v[104:105], off offset:32
	s_nop 0
	v_mul_f32_e32 v104, v101, v101
	global_store_dwordx4 v[176:177], v[100:103], off offset:512
	v_fmac_f32_e32 v104, v100, v100
	s_nop 0
	v_cvt_pk_bf16_f32 v100, v100, v101
	v_cvt_pk_bf16_f32 v101, v102, v103
	global_store_dwordx2 v[110:111], v[100:101], off offset:256
	s_nop 0
	v_mul_f32_e32 v100, v97, v97
	global_store_dwordx4 v[176:177], v[96:99], off offset:576
	v_fmac_f32_e32 v100, v96, v96
	v_mul_f32_e32 v101, v99, v99
	v_cvt_pk_bf16_f32 v96, v96, v97
	v_cvt_pk_bf16_f32 v97, v98, v99
	global_store_dwordx2 v[110:111], v[96:97], off offset:288
	v_lshlrev_b64 v[96:97], 11, v[174:175]
	s_nop 0
	s_nop 0
	v_fmac_f32_e32 v101, v98, v98
	v_lshl_add_u64 v[96:97], v[96:97], 0, v[164:165]
	v_mul_f32_e32 v98, v93, v93
	v_mul_f32_e32 v99, v95, v95
	global_store_dwordx4 v[178:179], v[92:95], off
	v_fmac_f32_e32 v98, v92, v92
	v_fmac_f32_e32 v99, v94, v94
	v_cvt_pk_bf16_f32 v92, v92, v93
	v_cvt_pk_bf16_f32 v93, v94, v95
	v_lshl_add_u64 v[94:95], v[96:97], 1, s[8:9]
	s_nop 0
	global_store_dwordx2 v[94:95], v[92:93], off
	s_nop 0
	v_mul_f32_e32 v92, v89, v89
	global_store_dwordx4 v[178:179], v[88:91], off offset:64
	v_fmac_f32_e32 v92, v88, v88
	s_nop 0
	v_cvt_pk_bf16_f32 v88, v88, v89
	v_cvt_pk_bf16_f32 v89, v90, v91
	global_store_dwordx2 v[94:95], v[88:89], off offset:32
	s_nop 0
	v_mul_f32_e32 v88, v85, v85
	global_store_dwordx4 v[178:179], v[84:87], off offset:512
	v_fmac_f32_e32 v88, v84, v84
	s_nop 0
	v_cvt_pk_bf16_f32 v84, v84, v85
	v_cvt_pk_bf16_f32 v85, v86, v87
	global_store_dwordx2 v[94:95], v[84:85], off offset:256
	s_nop 0
	v_mul_f32_e32 v84, v81, v81
	global_store_dwordx4 v[178:179], v[80:83], off offset:576
	v_fmac_f32_e32 v84, v80, v80
	v_mul_f32_e32 v85, v83, v83
	v_cvt_pk_bf16_f32 v80, v80, v81
	v_cvt_pk_bf16_f32 v81, v82, v83
	global_store_dwordx2 v[94:95], v[80:81], off offset:288
	v_lshlrev_b64 v[80:81], 11, v[170:171]
	s_nop 0
	s_nop 0
	v_fmac_f32_e32 v85, v82, v82
	v_lshl_add_u64 v[80:81], v[80:81], 0, v[164:165]
	v_mul_f32_e32 v82, v77, v77
	v_mul_f32_e32 v83, v79, v79
	global_store_dwordx4 v[172:173], v[76:79], off
	v_fmac_f32_e32 v82, v76, v76
	v_fmac_f32_e32 v83, v78, v78
	v_cvt_pk_bf16_f32 v76, v76, v77
	v_cvt_pk_bf16_f32 v77, v78, v79
	v_lshl_add_u64 v[78:79], v[80:81], 1, s[8:9]
	s_nop 0
	global_store_dwordx2 v[78:79], v[76:77], off
	s_nop 0
	v_mul_f32_e32 v76, v73, v73
	global_store_dwordx4 v[172:173], v[72:75], off offset:64
	v_fmac_f32_e32 v76, v72, v72
	v_mul_f32_e32 v77, v75, v75
	v_cvt_pk_bf16_f32 v72, v72, v73
	v_cvt_pk_bf16_f32 v73, v74, v75
	s_nop 0
	s_nop 0
	v_fmac_f32_e32 v77, v74, v74
	global_store_dwordx2 v[78:79], v[72:73], off offset:32
	v_mul_f32_e32 v72, v69, v69
	v_mul_f32_e32 v73, v71, v71
	v_add_f32_e32 v82, v82, v83
	v_add_f32_e32 v76, v76, v77
	v_fmac_f32_e32 v72, v68, v68
	v_fmac_f32_e32 v73, v70, v70
	v_add_f32_e32 v76, v82, v76
	v_add_f32_e32 v72, v72, v73
	v_add_f32_e32 v76, v76, v72
	v_mov_b64_e32 v[74:75], v[66:67]
	v_mov_b64_e32 v[72:73], v[64:65]
	v_mul_f32_e32 v65, v75, v75
	v_mul_f32_e32 v64, v73, v73
	v_fmac_f32_e32 v64, v72, v72
	v_fmac_f32_e32 v65, v74, v74
	global_store_dwordx4 v[172:173], v[68:71], off offset:512
	v_add_f32_e32 v64, v64, v65
	v_and_b32_e32 v65, 64, v186
	v_cvt_pk_bf16_f32 v68, v68, v69
	v_cvt_pk_bf16_f32 v69, v70, v71
	global_store_dwordx2 v[78:79], v[68:69], off offset:256
	v_add_f32_e32 v67, v76, v64
	v_xor_b32_e32 v64, 16, v186
	v_add_u32_e32 v68, 64, v65
	v_mul_f32_e32 v109, v107, v107
	v_mul_f32_e32 v93, v91, v91
	v_cmp_lt_i32_e32 vcc, v64, v68
	v_fmac_f32_e32 v109, v106, v106
	v_mul_f32_e32 v105, v103, v103
	v_fmac_f32_e32 v93, v90, v90
	v_mul_f32_e32 v89, v87, v87
	v_cndmask_b32_e32 v64, v186, v64, vcc
	v_add_f32_e32 v108, v108, v109
	v_fmac_f32_e32 v105, v102, v102
	v_add_f32_e32 v98, v98, v99
	v_add_f32_e32 v92, v92, v93
	v_fmac_f32_e32 v89, v86, v86
	v_lshlrev_b32_e32 v96, 2, v64
	v_add_f32_e32 v108, v113, v108
	v_add_f32_e32 v104, v104, v105
	v_add_f32_e32 v92, v98, v92
	v_add_f32_e32 v88, v88, v89
	ds_bpermute_b32 v69, v96, v67
	v_add_f32_e32 v104, v108, v104
	v_add_f32_e32 v100, v100, v101
	v_add_f32_e32 v88, v92, v88
	v_add_f32_e32 v84, v84, v85
	v_add_f32_e32 v100, v104, v100
	v_add_f32_e32 v84, v88, v84
	ds_bpermute_b32 v64, v96, v112
	ds_bpermute_b32 v65, v96, v100
	ds_bpermute_b32 v66, v96, v84
	s_waitcnt lgkmcnt(3)
	v_add_f32_e32 v67, v67, v69
	v_xor_b32_e32 v69, 32, v186
	v_cmp_lt_i32_e32 vcc, v69, v68
	s_waitcnt lgkmcnt(2)
	v_add_f32_e32 v64, v112, v64
	s_waitcnt lgkmcnt(1)
	v_add_f32_e32 v65, v100, v65
	v_cndmask_b32_e32 v68, v186, v69, vcc
	s_waitcnt lgkmcnt(0)
	v_add_f32_e32 v66, v84, v66
	v_lshlrev_b32_e32 v97, 2, v68
	ds_bpermute_b32 v68, v97, v64
	ds_bpermute_b32 v69, v97, v65
	ds_bpermute_b32 v70, v97, v66
	ds_bpermute_b32 v71, v97, v67
	v_lshl_add_u64 v[84:85], v[168:169], 2, s[10:11]
	global_store_dwordx4 v[172:173], v[72:75], off offset:576
	s_nop 1
	v_cvt_pk_bf16_f32 v72, v72, v73
	v_cvt_pk_bf16_f32 v73, v74, v75
	global_store_dwordx2 v[78:79], v[72:73], off offset:288
	s_and_saveexec_b64 s[38:39], s[2:3]
	s_cbranch_execz .LBB0_997
	s_waitcnt lgkmcnt(3)
	v_add_f32_e32 v64, v64, v68
	s_waitcnt lgkmcnt(0)
	v_add_f32_e32 v67, v67, v71
	v_add_f32_e32 v66, v66, v70
	v_add_f32_e32 v65, v65, v69
	global_atomic_add_f32 v[84:85], v64, off
	global_atomic_add_f32 v[84:85], v65, off offset:64
	global_atomic_add_f32 v[84:85], v66, off offset:128
	global_atomic_add_f32 v[84:85], v67, off offset:192
.LBB0_997:
	s_or_b64 exec, exec, s[38:39]
	v_add_u32_e32 v64, 0x80, v168
	v_ashrrev_i32_e32 v65, 31, v64
	v_lshlrev_b64 v[66:67], 13, v[64:65]
	v_lshl_add_u64 v[142:143], v[166:167], 0, v[66:67]
	s_nop 0
	s_nop 0
	s_nop 0
	s_nop 0
	v_add_u32_e32 v66, 0x90, v168
	v_ashrrev_i32_e32 v67, 31, v66
	s_waitcnt lgkmcnt(2)
	v_lshlrev_b64 v[68:69], 13, v[66:67]
	v_lshl_add_u64 v[92:93], v[166:167], 0, v[68:69]
	s_nop 0
	s_nop 0
	v_add_u32_e32 v90, 0xa0, v168
	v_add_u32_e32 v88, 0xb0, v168
	v_ashrrev_i32_e32 v91, 31, v90
	v_ashrrev_i32_e32 v89, 31, v88
	v_lshlrev_b64 v[68:69], 13, v[90:91]
	s_waitcnt lgkmcnt(0)
	v_lshlrev_b64 v[70:71], 13, v[88:89]
	v_lshlrev_b64 v[64:65], 11, v[64:65]
	v_lshlrev_b64 v[66:67], 11, v[66:67]
	v_lshl_add_u64 v[94:95], v[166:167], 0, v[68:69]
	v_lshl_add_u64 v[86:87], v[166:167], 0, v[70:71]
	v_lshl_add_u64 v[144:145], v[64:65], 0, v[164:165]
	v_lshl_add_u64 v[146:147], v[66:67], 0, v[164:165]
	s_nop 0
	s_nop 0
	s_nop 0
	s_nop 0
	s_nop 0
	s_nop 0
	s_nop 0
	s_nop 0
	s_nop 0
	s_nop 0
	v_lshl_add_u64 v[144:145], v[144:145], 1, s[8:9]
	s_nop 0
	s_nop 0
	s_nop 0
	s_nop 0
	s_nop 0
	s_nop 0
	s_nop 0
	s_nop 0
	s_nop 0
	global_store_dwordx4 v[142:143], v[60:63], off
	v_mul_f32_e32 v100, v61, v61
	v_mul_f32_e32 v101, v63, v63
	v_cvt_pk_bf16_f32 v98, v60, v61
	v_cvt_pk_bf16_f32 v99, v62, v63
	v_mul_f32_e32 v61, v57, v57
	v_mul_f32_e32 v63, v59, v59
	s_nop 0
	s_nop 0
	s_nop 0
	v_mul_f32_e32 v102, v49, v49
	v_mul_f32_e32 v103, v51, v51
	v_fmac_f32_e32 v100, v60, v60
	v_fmac_f32_e32 v101, v62, v62
	v_fmac_f32_e32 v61, v56, v56
	v_fmac_f32_e32 v63, v58, v58
	v_mul_f32_e32 v104, v45, v45
	v_mul_f32_e32 v105, v47, v47
	global_store_dwordx2 v[144:145], v[98:99], off
	global_store_dwordx4 v[142:143], v[56:59], off offset:64
	v_fmac_f32_e32 v102, v48, v48
	v_fmac_f32_e32 v103, v50, v50
	v_cvt_pk_bf16_f32 v56, v56, v57
	v_cvt_pk_bf16_f32 v57, v58, v59
	v_add_f32_e32 v58, v100, v101
	v_add_f32_e32 v59, v61, v63
	v_fmac_f32_e32 v104, v44, v44
	v_fmac_f32_e32 v105, v46, v46
	global_store_dwordx2 v[144:145], v[56:57], off offset:32
	global_store_dwordx4 v[142:143], v[48:51], off offset:512
	v_add_f32_e32 v56, v102, v103
	s_nop 0
	s_nop 0
	v_cvt_pk_bf16_f32 v48, v48, v49
	v_cvt_pk_bf16_f32 v49, v50, v51
	v_add_f32_e32 v51, v58, v59
	v_add_f32_e32 v50, v104, v105
	global_store_dwordx2 v[144:145], v[48:49], off offset:256
	global_store_dwordx4 v[142:143], v[44:47], off offset:576
	s_nop 0
	s_nop 0
	s_nop 0
	v_cvt_pk_bf16_f32 v44, v44, v45
	v_cvt_pk_bf16_f32 v45, v46, v47
	v_add_f32_e32 v46, v51, v56
	global_store_dwordx2 v[144:145], v[44:45], off offset:288
	global_store_dwordx4 v[92:93], v[52:55], off
	v_add_f32_e32 v48, v46, v50
	v_cvt_pk_bf16_f32 v44, v52, v53
	v_lshl_add_u64 v[46:47], v[146:147], 1, s[8:9]
	v_cvt_pk_bf16_f32 v45, v54, v55
	global_store_dwordx2 v[46:47], v[44:45], off
	s_nop 0
	v_mul_f32_e32 v44, v41, v41
	global_store_dwordx4 v[92:93], v[40:43], off offset:64
	v_fmac_f32_e32 v44, v40, v40
	s_nop 0
	s_nop 0
	v_cvt_pk_bf16_f32 v40, v40, v41
	v_cvt_pk_bf16_f32 v41, v42, v43
	global_store_dwordx2 v[46:47], v[40:41], off offset:32
	s_nop 0
	v_mul_f32_e32 v40, v37, v37
	global_store_dwordx4 v[92:93], v[36:39], off offset:512
	v_fmac_f32_e32 v40, v36, v36
	s_nop 0
	s_nop 0
	v_cvt_pk_bf16_f32 v36, v36, v37
	v_cvt_pk_bf16_f32 v37, v38, v39
	global_store_dwordx2 v[46:47], v[36:37], off offset:256
	s_nop 0
	v_mul_f32_e32 v36, v33, v33
	global_store_dwordx4 v[92:93], v[32:35], off offset:576
	v_fmac_f32_e32 v36, v32, v32
	v_mul_f32_e32 v37, v35, v35
	v_cvt_pk_bf16_f32 v32, v32, v33
	v_cvt_pk_bf16_f32 v33, v34, v35
	global_store_dwordx2 v[46:47], v[32:33], off offset:288
	v_lshlrev_b64 v[32:33], 11, v[90:91]
	s_nop 0
	s_nop 0
	s_nop 0
	v_fmac_f32_e32 v37, v34, v34
	v_lshl_add_u64 v[32:33], v[32:33], 0, v[164:165]
	v_mul_f32_e32 v34, v29, v29
	v_mul_f32_e32 v35, v31, v31
	global_store_dwordx4 v[94:95], v[28:31], off
	v_fmac_f32_e32 v34, v28, v28
	v_fmac_f32_e32 v35, v30, v30
	v_cvt_pk_bf16_f32 v28, v28, v29
	v_cvt_pk_bf16_f32 v29, v30, v31
	v_lshl_add_u64 v[30:31], v[32:33], 1, s[8:9]
	s_nop 0
	s_nop 0
	global_store_dwordx2 v[30:31], v[28:29], off
	s_nop 0
	v_mul_f32_e32 v28, v25, v25
	global_store_dwordx4 v[94:95], v[24:27], off offset:64
	v_fmac_f32_e32 v28, v24, v24
	s_nop 0
	s_nop 0
	v_cvt_pk_bf16_f32 v24, v24, v25
	v_cvt_pk_bf16_f32 v25, v26, v27
	global_store_dwordx2 v[30:31], v[24:25], off offset:32
	s_nop 0
	v_mul_f32_e32 v24, v21, v21
	global_store_dwordx4 v[94:95], v[20:23], off offset:512
	v_fmac_f32_e32 v24, v20, v20
	s_nop 0
	s_nop 0
	v_cvt_pk_bf16_f32 v20, v20, v21
	v_cvt_pk_bf16_f32 v21, v22, v23
	global_store_dwordx2 v[30:31], v[20:21], off offset:256
	s_nop 0
	v_mul_f32_e32 v20, v17, v17
	global_store_dwordx4 v[94:95], v[16:19], off offset:576
	v_fmac_f32_e32 v20, v16, v16
	v_mul_f32_e32 v21, v19, v19
	v_cvt_pk_bf16_f32 v16, v16, v17
	v_cvt_pk_bf16_f32 v17, v18, v19
	global_store_dwordx2 v[30:31], v[16:17], off offset:288
	v_lshlrev_b64 v[16:17], 11, v[88:89]
	s_nop 0
	s_nop 0
	s_nop 0
	v_fmac_f32_e32 v21, v18, v18
	v_lshl_add_u64 v[16:17], v[16:17], 0, v[164:165]
	v_mul_f32_e32 v18, v13, v13
	v_mul_f32_e32 v19, v15, v15
	global_store_dwordx4 v[86:87], v[12:15], off
	v_fmac_f32_e32 v18, v12, v12
	v_fmac_f32_e32 v19, v14, v14
	v_cvt_pk_bf16_f32 v12, v12, v13
	v_cvt_pk_bf16_f32 v13, v14, v15
	v_lshl_add_u64 v[14:15], v[16:17], 1, s[8:9]
	s_nop 0
	s_nop 0
	global_store_dwordx2 v[14:15], v[12:13], off
	s_nop 0
	v_mul_f32_e32 v12, v9, v9
	global_store_dwordx4 v[86:87], v[8:11], off offset:64
	v_fmac_f32_e32 v12, v8, v8
	v_mul_f32_e32 v13, v11, v11
	v_cvt_pk_bf16_f32 v8, v8, v9
	v_cvt_pk_bf16_f32 v9, v10, v11
	s_nop 0
	s_nop 0
	s_nop 0
	v_fmac_f32_e32 v13, v10, v10
	global_store_dwordx2 v[14:15], v[8:9], off offset:32
	v_mul_f32_e32 v8, v5, v5
	v_mul_f32_e32 v9, v7, v7
	v_add_f32_e32 v18, v18, v19
	v_add_f32_e32 v12, v12, v13
	v_fmac_f32_e32 v8, v4, v4
	v_fmac_f32_e32 v9, v6, v6
	v_mul_f32_e32 v106, v53, v53
	v_mul_f32_e32 v107, v55, v55
	v_mul_f32_e32 v45, v43, v43
	v_mul_f32_e32 v29, v27, v27
	v_add_f32_e32 v12, v18, v12
	v_add_f32_e32 v8, v8, v9
	v_fmac_f32_e32 v106, v52, v52
	v_fmac_f32_e32 v107, v54, v54
	v_fmac_f32_e32 v45, v42, v42
	v_mul_f32_e32 v41, v39, v39
	v_fmac_f32_e32 v29, v26, v26
	v_mul_f32_e32 v25, v23, v23
	v_add_f32_e32 v12, v12, v8
	s_nop 0
	v_mov_b64_e32 v[10:11], v[2:3]
	v_mov_b64_e32 v[8:9], v[0:1]
	v_add_f32_e32 v49, v106, v107
	v_add_f32_e32 v44, v44, v45
	v_fmac_f32_e32 v41, v38, v38
	v_add_f32_e32 v34, v34, v35
	v_add_f32_e32 v28, v28, v29
	v_fmac_f32_e32 v25, v22, v22
	v_mul_f32_e32 v0, v9, v9
	v_mul_f32_e32 v1, v11, v11
	v_add_f32_e32 v44, v49, v44
	v_add_f32_e32 v40, v40, v41
	v_add_f32_e32 v28, v34, v28
	v_add_f32_e32 v24, v24, v25
	v_fmac_f32_e32 v0, v8, v8
	v_fmac_f32_e32 v1, v10, v10
	v_add_f32_e32 v40, v44, v40
	v_add_f32_e32 v36, v36, v37
	v_add_f32_e32 v24, v28, v24
	v_add_f32_e32 v20, v20, v21
	v_add_f32_e32 v0, v0, v1
	v_add_f32_e32 v36, v40, v36
	v_add_f32_e32 v20, v24, v20
	v_add_f32_e32 v3, v12, v0
	global_store_dwordx4 v[86:87], v[4:7], off offset:512
	ds_bpermute_b32 v0, v96, v48
	ds_bpermute_b32 v1, v96, v36
	v_cvt_pk_bf16_f32 v4, v4, v5
	v_cvt_pk_bf16_f32 v5, v6, v7
	ds_bpermute_b32 v2, v96, v20
	ds_bpermute_b32 v6, v96, v3
	global_store_dwordx2 v[14:15], v[4:5], off offset:256
	s_waitcnt lgkmcnt(3)
	v_add_f32_e32 v0, v48, v0
	s_waitcnt lgkmcnt(2)
	v_add_f32_e32 v1, v36, v1
	s_waitcnt lgkmcnt(1)
	v_add_f32_e32 v2, v20, v2
	s_waitcnt lgkmcnt(0)
	v_add_f32_e32 v4, v3, v6
	ds_bpermute_b32 v3, v97, v0
	ds_bpermute_b32 v5, v97, v1
	ds_bpermute_b32 v6, v97, v2
	ds_bpermute_b32 v7, v97, v4
	global_store_dwordx4 v[86:87], v[8:11], off offset:576
	s_nop 1
	v_cvt_pk_bf16_f32 v8, v8, v9
	v_cvt_pk_bf16_f32 v9, v10, v11
	global_store_dwordx2 v[14:15], v[8:9], off offset:288
	s_and_saveexec_b64 s[38:39], s[2:3]
	s_cbranch_execz .LBB0_999
	s_waitcnt lgkmcnt(3)
	v_add_f32_e32 v0, v0, v3
	s_waitcnt lgkmcnt(0)
	v_add_f32_e32 v4, v4, v7
	v_add_f32_e32 v2, v2, v6
	v_add_f32_e32 v1, v1, v5
	global_atomic_add_f32 v[84:85], v0, off offset:512
	global_atomic_add_f32 v[84:85], v1, off offset:576
	global_atomic_add_f32 v[84:85], v2, off offset:640
	global_atomic_add_f32 v[84:85], v4, off offset:704

.LBB0_1472:
	s_ashr_i32 s19, s18, 31
	s_lshl_b64 s[34:35], s[18:19], 20
	s_add_u32 s34, s54, s34
	s_addc_u32 s35, s55, s35
	s_and_b64 s[6:7], s[6:7], exec
	s_cselect_b32 s19, s35, s39
	s_cselect_b32 s69, s34, s38
	s_add_u32 s70, s38, 0x100
	s_addc_u32 s71, s39, 0
	s_mov_b32 s72, -2
	s_waitcnt lgkmcnt(0)
	s_waitcnt vmcnt(0)
	v_readlane_b32 s98, v248, 6
	v_readlane_b32 s99, v248, 7
	v_lshl_add_u32 v249, s67, 8, v180
	v_lshl_or_b32 v250, s68, 8, v182
	v_lshlrev_b32_e32 v249, 13, v249
	v_lshl_add_u32 v249, v250, 2, v249
	s_nop 1
	global_load_dwordx4 v[124:127], v249, s[98:99]
	global_load_dwordx4 v[120:123], v249, s[98:99] offset:64
	global_load_dwordx4 v[112:115], v249, s[98:99] offset:512
	global_load_dwordx4 v[108:111], v249, s[98:99] offset:576
	v_add_u32_e32 v249, 0x20000, v249
	global_load_dwordx4 v[116:119], v249, s[98:99]
	global_load_dwordx4 v[104:107], v249, s[98:99] offset:64
	global_load_dwordx4 v[100:103], v249, s[98:99] offset:512
	global_load_dwordx4 v[96:99], v249, s[98:99] offset:576
	v_add_u32_e32 v249, 0x20000, v249
	global_load_dwordx4 v[92:95], v249, s[98:99]
	global_load_dwordx4 v[88:91], v249, s[98:99] offset:64
	global_load_dwordx4 v[84:87], v249, s[98:99] offset:512
	global_load_dwordx4 v[80:83], v249, s[98:99] offset:576
	v_add_u32_e32 v249, 0x20000, v249
	global_load_dwordx4 v[76:79], v249, s[98:99]
	global_load_dwordx4 v[72:75], v249, s[98:99] offset:64
	global_load_dwordx4 v[68:71], v249, s[98:99] offset:512
	global_load_dwordx4 v[64:67], v249, s[98:99] offset:576
	v_add_u32_e32 v249, 0xa0000, v249
	global_load_dwordx4 v[60:63], v249, s[98:99]
	global_load_dwordx4 v[56:59], v249, s[98:99] offset:64
	global_load_dwordx4 v[48:51], v249, s[98:99] offset:512
	global_load_dwordx4 v[44:47], v249, s[98:99] offset:576
	v_add_u32_e32 v249, 0x20000, v249
	global_load_dwordx4 v[52:55], v249, s[98:99]
	global_load_dwordx4 v[40:43], v249, s[98:99] offset:64
	global_load_dwordx4 v[36:39], v249, s[98:99] offset:512
	global_load_dwordx4 v[32:35], v249, s[98:99] offset:576
	v_add_u32_e32 v249, 0x20000, v249
	global_load_dwordx4 v[28:31], v249, s[98:99]
	global_load_dwordx4 v[24:27], v249, s[98:99] offset:64
	global_load_dwordx4 v[20:23], v249, s[98:99] offset:512
	global_load_dwordx4 v[16:19], v249, s[98:99] offset:576
	v_add_u32_e32 v249, 0x20000, v249
	global_load_dwordx4 v[12:15], v249, s[98:99]
	global_load_dwordx4 v[8:11], v249, s[98:99] offset:64
	global_load_dwordx4 v[4:7], v249, s[98:99] offset:512
	global_load_dwordx4 v[0:3], v249, s[98:99] offset:576

.LBB0_1476:
	v_lshl_add_u32 v168, s67, 8, v180
	v_lshl_or_b32 v164, s68, 8, v182
	v_readlane_b32 s68, v248, 0
	v_ashrrev_i32_e32 v165, 31, v164
	v_ashrrev_i32_e32 v169, 31, v168
	v_readlane_b32 s74, v248, 6
	v_readlane_b32 s75, v248, 7
	v_lshlrev_b64 v[128:129], 13, v[168:169]
	v_or_b32_e32 v174, 32, v168
	v_lshl_add_u64 v[166:167], v[164:165], 2, s[74:75]
	v_lshl_add_u64 v[218:219], v[166:167], 0, v[128:129]
	v_or_b32_e32 v128, 16, v168
	v_ashrrev_i32_e32 v129, 31, v128
	s_nop 0
	s_nop 0
	s_nop 0
	s_nop 0
	v_lshlrev_b64 v[130:131], 13, v[128:129]
	v_lshl_add_u64 v[176:177], v[166:167], 0, v[130:131]
	s_nop 0
	s_nop 0
	v_or_b32_e32 v170, 48, v168
	v_ashrrev_i32_e32 v175, 31, v174
	v_ashrrev_i32_e32 v171, 31, v170
	v_lshlrev_b64 v[130:131], 11, v[168:169]
	v_lshlrev_b64 v[132:133], 13, v[174:175]
	v_lshlrev_b64 v[134:135], 13, v[170:171]
	v_lshl_add_u64 v[130:131], v[130:131], 0, v[164:165]
	v_lshlrev_b64 v[128:129], 11, v[128:129]
	v_lshl_add_u64 v[178:179], v[166:167], 0, v[132:133]
	v_lshl_add_u64 v[172:173], v[166:167], 0, v[134:135]
	v_lshl_add_u64 v[234:235], v[130:131], 1, s[10:11]
	v_lshl_add_u64 v[236:237], v[128:129], 0, v[164:165]
	s_nop 0
	s_nop 0
	s_nop 0
	s_nop 0
	s_nop 0
	s_nop 0
	s_nop 0
	s_nop 0
	s_nop 0
	s_nop 0
	v_readlane_b32 s69, v248, 1
	v_readlane_b32 s70, v248, 2
	v_readlane_b32 s71, v248, 3
	v_readlane_b32 s72, v248, 4
	v_readlane_b32 s73, v248, 5
	s_nop 0
	s_nop 0
	s_nop 0
	s_nop 0
	s_nop 0
	s_nop 0
	global_store_dwordx4 v[218:219], v[124:127], off
	v_mul_f32_e32 v188, v125, v125
	v_cvt_pk_bf16_f32 v186, v124, v125
	v_cvt_pk_bf16_f32 v187, v126, v127
	s_nop 0
	v_mul_f32_e32 v125, v121, v121
	s_nop 0
	v_mul_f32_e32 v189, v127, v127
	v_mul_f32_e32 v127, v123, v123
	v_mul_f32_e32 v190, v113, v113
	global_store_dwordx2 v[234:235], v[186:187], off
	global_store_dwordx4 v[218:219], v[120:123], off offset:64
	v_fmac_f32_e32 v125, v120, v120
	s_nop 0
	v_cvt_pk_bf16_f32 v120, v120, v121
	v_cvt_pk_bf16_f32 v121, v122, v123
	v_mul_f32_e32 v191, v115, v115
	v_mul_f32_e32 v192, v109, v109
	v_fmac_f32_e32 v188, v124, v124
	v_fmac_f32_e32 v189, v126, v126
	v_fmac_f32_e32 v127, v122, v122
	v_fmac_f32_e32 v190, v112, v112
	global_store_dwordx2 v[234:235], v[120:121], off offset:32
	global_store_dwordx4 v[218:219], v[112:115], off offset:512
	v_mul_f32_e32 v193, v111, v111
	s_nop 0
	v_cvt_pk_bf16_f32 v112, v112, v113
	v_cvt_pk_bf16_f32 v113, v114, v115
	s_nop 0
	v_fmac_f32_e32 v191, v114, v114
	v_fmac_f32_e32 v192, v108, v108
	v_add_f32_e32 v123, v188, v189
	v_add_f32_e32 v124, v125, v127
	global_store_dwordx2 v[234:235], v[112:113], off offset:256
	global_store_dwordx4 v[218:219], v[108:111], off offset:576
	v_fmac_f32_e32 v193, v110, v110
	v_mul_f32_e32 v122, v117, v117
	v_cvt_pk_bf16_f32 v108, v108, v109
	v_cvt_pk_bf16_f32 v109, v110, v111
	v_add_f32_e32 v120, v190, v191
	v_add_f32_e32 v115, v123, v124
	global_store_dwordx2 v[234:235], v[108:109], off offset:288
	global_store_dwordx4 v[176:177], v[116:119], off
	v_mul_f32_e32 v108, v119, v119
	v_add_f32_e32 v114, v192, v193
	v_add_f32_e32 v110, v115, v120
	v_fmac_f32_e32 v122, v116, v116
	v_fmac_f32_e32 v108, v118, v118
	v_add_f32_e32 v112, v110, v114
	v_add_f32_e32 v113, v122, v108
	v_cvt_pk_bf16_f32 v108, v116, v117
	v_lshl_add_u64 v[110:111], v[236:237], 1, s[10:11]
	s_nop 0
	v_cvt_pk_bf16_f32 v109, v118, v119
	global_store_dwordx2 v[110:111], v[108:109], off
	s_nop 0
	v_mul_f32_e32 v108, v105, v105
	global_store_dwordx4 v[176:177], v[104:107], off offset:64
	v_fmac_f32_e32 v108, v104, v104
	s_nop 0
	v_cvt_pk_bf16_f32 v104, v104, v105
	v_cvt_pk_bf16_f32 v105, v106, v107
	global_store_dwordx2 v[110:111], v[104:105], off offset:32
	s_nop 0
	v_mul_f32_e32 v104, v101, v101
	global_store_dwordx4 v[176:177], v[100:103], off offset:512
	v_fmac_f32_e32 v104, v100, v100
	s_nop 0
	v_cvt_pk_bf16_f32 v100, v100, v101
	v_cvt_pk_bf16_f32 v101, v102, v103
	global_store_dwordx2 v[110:111], v[100:101], off offset:256
	s_nop 0
	v_mul_f32_e32 v100, v97, v97
	global_store_dwordx4 v[176:177], v[96:99], off offset:576
	v_fmac_f32_e32 v100, v96, v96
	v_mul_f32_e32 v101, v99, v99
	v_cvt_pk_bf16_f32 v96, v96, v97
	v_cvt_pk_bf16_f32 v97, v98, v99
	global_store_dwordx2 v[110:111], v[96:97], off offset:288
	v_lshlrev_b64 v[96:97], 11, v[174:175]
	s_nop 0
	s_nop 0
	v_fmac_f32_e32 v101, v98, v98
	v_lshl_add_u64 v[96:97], v[96:97], 0, v[164:165]
	v_mul_f32_e32 v98, v93, v93
	v_mul_f32_e32 v99, v95, v95
	global_store_dwordx4 v[178:179], v[92:95], off
	v_fmac_f32_e32 v98, v92, v92
	v_fmac_f32_e32 v99, v94, v94
	v_cvt_pk_bf16_f32 v92, v92, v93
	v_cvt_pk_bf16_f32 v93, v94, v95
	v_lshl_add_u64 v[94:95], v[96:97], 1, s[10:11]
	s_nop 0
	global_store_dwordx2 v[94:95], v[92:93], off
	s_nop 0
	v_mul_f32_e32 v92, v89, v89
	global_store_dwordx4 v[178:179], v[88:91], off offset:64
	v_fmac_f32_e32 v92, v88, v88
	s_nop 0
	v_cvt_pk_bf16_f32 v88, v88, v89
	v_cvt_pk_bf16_f32 v89, v90, v91
	global_store_dwordx2 v[94:95], v[88:89], off offset:32
	s_nop 0
	v_mul_f32_e32 v88, v85, v85
	global_store_dwordx4 v[178:179], v[84:87], off offset:512
	v_fmac_f32_e32 v88, v84, v84
	s_nop 0
	v_cvt_pk_bf16_f32 v84, v84, v85
	v_cvt_pk_bf16_f32 v85, v86, v87
	global_store_dwordx2 v[94:95], v[84:85], off offset:256
	s_nop 0
	v_mul_f32_e32 v84, v81, v81
	global_store_dwordx4 v[178:179], v[80:83], off offset:576
	v_fmac_f32_e32 v84, v80, v80
	v_mul_f32_e32 v85, v83, v83
	v_cvt_pk_bf16_f32 v80, v80, v81
	v_cvt_pk_bf16_f32 v81, v82, v83
	global_store_dwordx2 v[94:95], v[80:81], off offset:288
	v_lshlrev_b64 v[80:81], 11, v[170:171]
	s_nop 0
	s_nop 0
	v_fmac_f32_e32 v85, v82, v82
	v_lshl_add_u64 v[80:81], v[80:81], 0, v[164:165]
	v_mul_f32_e32 v82, v77, v77
	v_mul_f32_e32 v83, v79, v79
	global_store_dwordx4 v[172:173], v[76:79], off
	v_fmac_f32_e32 v82, v76, v76
	v_fmac_f32_e32 v83, v78, v78
	v_cvt_pk_bf16_f32 v76, v76, v77
	v_cvt_pk_bf16_f32 v77, v78, v79
	v_lshl_add_u64 v[78:79], v[80:81], 1, s[10:11]
	s_nop 0
	global_store_dwordx2 v[78:79], v[76:77], off
	s_nop 0
	v_mul_f32_e32 v76, v73, v73
	global_store_dwordx4 v[172:173], v[72:75], off offset:64
	v_fmac_f32_e32 v76, v72, v72
	v_mul_f32_e32 v77, v75, v75
	v_cvt_pk_bf16_f32 v72, v72, v73
	v_cvt_pk_bf16_f32 v73, v74, v75
	s_nop 0
	s_nop 0
	v_fmac_f32_e32 v77, v74, v74
	global_store_dwordx2 v[78:79], v[72:73], off offset:32
	v_mul_f32_e32 v72, v69, v69
	v_mul_f32_e32 v73, v71, v71
	v_add_f32_e32 v82, v82, v83
	v_add_f32_e32 v76, v76, v77
	v_fmac_f32_e32 v72, v68, v68
	v_fmac_f32_e32 v73, v70, v70
	v_add_f32_e32 v76, v82, v76
	v_add_f32_e32 v72, v72, v73
	v_add_f32_e32 v76, v76, v72
	v_mov_b64_e32 v[74:75], v[66:67]
	v_mov_b64_e32 v[72:73], v[64:65]
	v_mul_f32_e32 v65, v75, v75
	v_mul_f32_e32 v64, v73, v73
	v_fmac_f32_e32 v64, v72, v72
	v_fmac_f32_e32 v65, v74, v74
	global_store_dwordx4 v[172:173], v[68:71], off offset:512
	v_add_f32_e32 v64, v64, v65
	v_and_b32_e32 v65, 64, v185
	v_cvt_pk_bf16_f32 v68, v68, v69
	v_cvt_pk_bf16_f32 v69, v70, v71
	global_store_dwordx2 v[78:79], v[68:69], off offset:256
	v_add_f32_e32 v67, v76, v64
	v_xor_b32_e32 v64, 16, v185
	v_add_u32_e32 v68, 64, v65
	v_mul_f32_e32 v109, v107, v107
	v_mul_f32_e32 v93, v91, v91
	v_cmp_lt_i32_e32 vcc, v64, v68
	v_fmac_f32_e32 v109, v106, v106
	v_mul_f32_e32 v105, v103, v103
	v_fmac_f32_e32 v93, v90, v90
	v_mul_f32_e32 v89, v87, v87
	v_cndmask_b32_e32 v64, v185, v64, vcc
	v_add_f32_e32 v108, v108, v109
	v_fmac_f32_e32 v105, v102, v102
	v_add_f32_e32 v98, v98, v99
	v_add_f32_e32 v92, v92, v93
	v_fmac_f32_e32 v89, v86, v86
	v_lshlrev_b32_e32 v96, 2, v64
	v_add_f32_e32 v108, v113, v108
	v_add_f32_e32 v104, v104, v105
	v_add_f32_e32 v92, v98, v92
	v_add_f32_e32 v88, v88, v89
	ds_bpermute_b32 v69, v96, v67
	v_add_f32_e32 v104, v108, v104
	v_add_f32_e32 v100, v100, v101
	v_add_f32_e32 v88, v92, v88
	v_add_f32_e32 v84, v84, v85
	v_add_f32_e32 v100, v104, v100
	v_add_f32_e32 v84, v88, v84
	ds_bpermute_b32 v64, v96, v112
	ds_bpermute_b32 v65, v96, v100
	ds_bpermute_b32 v66, v96, v84
	s_waitcnt lgkmcnt(3)
	v_add_f32_e32 v67, v67, v69
	v_xor_b32_e32 v69, 32, v185
	v_cmp_lt_i32_e32 vcc, v69, v68
	s_waitcnt lgkmcnt(2)
	v_add_f32_e32 v64, v112, v64
	s_waitcnt lgkmcnt(1)
	v_add_f32_e32 v65, v100, v65
	v_cndmask_b32_e32 v68, v185, v69, vcc
	s_waitcnt lgkmcnt(0)
	v_add_f32_e32 v66, v84, v66
	v_lshlrev_b32_e32 v97, 2, v68
	ds_bpermute_b32 v68, v97, v64
	ds_bpermute_b32 v69, v97, v65
	ds_bpermute_b32 v70, v97, v66
	ds_bpermute_b32 v71, v97, v67
	v_lshl_add_u64 v[84:85], v[168:169], 2, s[12:13]
	global_store_dwordx4 v[172:173], v[72:75], off offset:576
	s_nop 1
	v_cvt_pk_bf16_f32 v72, v72, v73
	v_cvt_pk_bf16_f32 v73, v74, v75
	global_store_dwordx2 v[78:79], v[72:73], off offset:288
	s_and_saveexec_b64 s[6:7], s[2:3]
	s_cbranch_execz .LBB0_1478
	s_waitcnt lgkmcnt(3)
	v_add_f32_e32 v64, v64, v68
	s_waitcnt lgkmcnt(0)
	v_add_f32_e32 v67, v67, v71
	v_add_f32_e32 v66, v66, v70
	v_add_f32_e32 v65, v65, v69
	global_atomic_add_f32 v[84:85], v64, off
	global_atomic_add_f32 v[84:85], v65, off offset:64
	global_atomic_add_f32 v[84:85], v66, off offset:128
	global_atomic_add_f32 v[84:85], v67, off offset:192
.LBB0_1478:
	s_or_b64 exec, exec, s[6:7]
	v_add_u32_e32 v64, 0x80, v168
	v_ashrrev_i32_e32 v65, 31, v64
	v_lshlrev_b64 v[66:67], 13, v[64:65]
	v_lshl_add_u64 v[142:143], v[166:167], 0, v[66:67]
	s_nop 0
	s_nop 0
	s_nop 0
	s_nop 0
	v_add_u32_e32 v66, 0x90, v168
	v_ashrrev_i32_e32 v67, 31, v66
	s_waitcnt lgkmcnt(2)
	v_lshlrev_b64 v[68:69], 13, v[66:67]
	v_lshl_add_u64 v[92:93], v[166:167], 0, v[68:69]
	s_nop 0
	s_nop 0
	v_add_u32_e32 v90, 0xa0, v168
	v_add_u32_e32 v88, 0xb0, v168
	v_ashrrev_i32_e32 v91, 31, v90
	v_ashrrev_i32_e32 v89, 31, v88
	v_lshlrev_b64 v[68:69], 13, v[90:91]
	s_waitcnt lgkmcnt(0)
	v_lshlrev_b64 v[70:71], 13, v[88:89]
	v_lshlrev_b64 v[64:65], 11, v[64:65]
	v_lshlrev_b64 v[66:67], 11, v[66:67]
	v_lshl_add_u64 v[94:95], v[166:167], 0, v[68:69]
	v_lshl_add_u64 v[86:87], v[166:167], 0, v[70:71]
	v_lshl_add_u64 v[144:145], v[64:65], 0, v[164:165]
	v_lshl_add_u64 v[146:147], v[66:67], 0, v[164:165]
	s_nop 0
	s_nop 0
	s_nop 0
	s_nop 0
	s_nop 0
	s_nop 0
	s_nop 0
	s_nop 0
	s_nop 0
	s_nop 0
	v_lshl_add_u64 v[144:145], v[144:145], 1, s[10:11]
	s_nop 0
	s_nop 0
	s_nop 0
	s_nop 0
	s_nop 0
	s_nop 0
	s_nop 0
	s_nop 0
	s_nop 0
	global_store_dwordx4 v[142:143], v[60:63], off
	v_mul_f32_e32 v100, v61, v61
	v_mul_f32_e32 v101, v63, v63
	v_cvt_pk_bf16_f32 v98, v60, v61
	v_cvt_pk_bf16_f32 v99, v62, v63
	v_mul_f32_e32 v61, v57, v57
	v_mul_f32_e32 v63, v59, v59
	s_nop 0
	s_nop 0
	s_nop 0
	v_mul_f32_e32 v102, v49, v49
	v_mul_f32_e32 v103, v51, v51
	v_fmac_f32_e32 v100, v60, v60
	v_fmac_f32_e32 v101, v62, v62
	v_fmac_f32_e32 v61, v56, v56
	v_fmac_f32_e32 v63, v58, v58
	v_mul_f32_e32 v104, v45, v45
	v_mul_f32_e32 v105, v47, v47
	global_store_dwordx2 v[144:145], v[98:99], off
	global_store_dwordx4 v[142:143], v[56:59], off offset:64
	v_fmac_f32_e32 v102, v48, v48
	v_fmac_f32_e32 v103, v50, v50
	v_cvt_pk_bf16_f32 v56, v56, v57
	v_cvt_pk_bf16_f32 v57, v58, v59
	v_add_f32_e32 v58, v100, v101
	v_add_f32_e32 v59, v61, v63
	v_fmac_f32_e32 v104, v44, v44
	v_fmac_f32_e32 v105, v46, v46
	global_store_dwordx2 v[144:145], v[56:57], off offset:32
	global_store_dwordx4 v[142:143], v[48:51], off offset:512
	v_add_f32_e32 v56, v102, v103
	s_nop 0
	s_nop 0
	v_cvt_pk_bf16_f32 v48, v48, v49
	v_cvt_pk_bf16_f32 v49, v50, v51
	v_add_f32_e32 v51, v58, v59
	v_add_f32_e32 v50, v104, v105
	global_store_dwordx2 v[144:145], v[48:49], off offset:256
	global_store_dwordx4 v[142:143], v[44:47], off offset:576
	s_nop 0
	s_nop 0
	s_nop 0
	v_cvt_pk_bf16_f32 v44, v44, v45
	v_cvt_pk_bf16_f32 v45, v46, v47
	v_add_f32_e32 v46, v51, v56
	global_store_dwordx2 v[144:145], v[44:45], off offset:288
	global_store_dwordx4 v[92:93], v[52:55], off
	v_add_f32_e32 v48, v46, v50
	v_cvt_pk_bf16_f32 v44, v52, v53
	v_lshl_add_u64 v[46:47], v[146:147], 1, s[10:11]
	v_cvt_pk_bf16_f32 v45, v54, v55
	global_store_dwordx2 v[46:47], v[44:45], off
	s_nop 0
	v_mul_f32_e32 v44, v41, v41
	global_store_dwordx4 v[92:93], v[40:43], off offset:64
	v_fmac_f32_e32 v44, v40, v40
	s_nop 0
	s_nop 0
	v_cvt_pk_bf16_f32 v40, v40, v41
	v_cvt_pk_bf16_f32 v41, v42, v43
	global_store_dwordx2 v[46:47], v[40:41], off offset:32
	s_nop 0
	v_mul_f32_e32 v40, v37, v37
	global_store_dwordx4 v[92:93], v[36:39], off offset:512
	v_fmac_f32_e32 v40, v36, v36
	s_nop 0
	s_nop 0
	v_cvt_pk_bf16_f32 v36, v36, v37
	v_cvt_pk_bf16_f32 v37, v38, v39
	global_store_dwordx2 v[46:47], v[36:37], off offset:256
	s_nop 0
	v_mul_f32_e32 v36, v33, v33
	global_store_dwordx4 v[92:93], v[32:35], off offset:576
	v_fmac_f32_e32 v36, v32, v32
	v_mul_f32_e32 v37, v35, v35
	v_cvt_pk_bf16_f32 v32, v32, v33
	v_cvt_pk_bf16_f32 v33, v34, v35
	global_store_dwordx2 v[46:47], v[32:33], off offset:288
	v_lshlrev_b64 v[32:33], 11, v[90:91]
	s_nop 0
	s_nop 0
	s_nop 0
	v_fmac_f32_e32 v37, v34, v34
	v_lshl_add_u64 v[32:33], v[32:33], 0, v[164:165]
	v_mul_f32_e32 v34, v29, v29
	v_mul_f32_e32 v35, v31, v31
	global_store_dwordx4 v[94:95], v[28:31], off
	v_fmac_f32_e32 v34, v28, v28
	v_fmac_f32_e32 v35, v30, v30
	v_cvt_pk_bf16_f32 v28, v28, v29
	v_cvt_pk_bf16_f32 v29, v30, v31
	v_lshl_add_u64 v[30:31], v[32:33], 1, s[10:11]
	s_nop 0
	s_nop 0
	global_store_dwordx2 v[30:31], v[28:29], off
	s_nop 0
	v_mul_f32_e32 v28, v25, v25
	global_store_dwordx4 v[94:95], v[24:27], off offset:64
	v_fmac_f32_e32 v28, v24, v24
	s_nop 0
	s_nop 0
	v_cvt_pk_bf16_f32 v24, v24, v25
	v_cvt_pk_bf16_f32 v25, v26, v27
	global_store_dwordx2 v[30:31], v[24:25], off offset:32
	s_nop 0
	v_mul_f32_e32 v24, v21, v21
	global_store_dwordx4 v[94:95], v[20:23], off offset:512
	v_fmac_f32_e32 v24, v20, v20
	s_nop 0
	s_nop 0
	v_cvt_pk_bf16_f32 v20, v20, v21
	v_cvt_pk_bf16_f32 v21, v22, v23
	global_store_dwordx2 v[30:31], v[20:21], off offset:256
	s_nop 0
	v_mul_f32_e32 v20, v17, v17
	global_store_dwordx4 v[94:95], v[16:19], off offset:576
	v_fmac_f32_e32 v20, v16, v16
	v_mul_f32_e32 v21, v19, v19
	v_cvt_pk_bf16_f32 v16, v16, v17
	v_cvt_pk_bf16_f32 v17, v18, v19
	global_store_dwordx2 v[30:31], v[16:17], off offset:288
	v_lshlrev_b64 v[16:17], 11, v[88:89]
	s_nop 0
	s_nop 0
	s_nop 0
	v_fmac_f32_e32 v21, v18, v18
	v_lshl_add_u64 v[16:17], v[16:17], 0, v[164:165]
	v_mul_f32_e32 v18, v13, v13
	v_mul_f32_e32 v19, v15, v15
	global_store_dwordx4 v[86:87], v[12:15], off
	v_fmac_f32_e32 v18, v12, v12
	v_fmac_f32_e32 v19, v14, v14
	v_cvt_pk_bf16_f32 v12, v12, v13
	v_cvt_pk_bf16_f32 v13, v14, v15
	v_lshl_add_u64 v[14:15], v[16:17], 1, s[10:11]
	s_nop 0
	s_nop 0
	global_store_dwordx2 v[14:15], v[12:13], off
	s_nop 0
	v_mul_f32_e32 v12, v9, v9
	global_store_dwordx4 v[86:87], v[8:11], off offset:64
	v_fmac_f32_e32 v12, v8, v8
	v_mul_f32_e32 v13, v11, v11
	v_cvt_pk_bf16_f32 v8, v8, v9
	v_cvt_pk_bf16_f32 v9, v10, v11
	s_nop 0
	s_nop 0
	s_nop 0
	v_fmac_f32_e32 v13, v10, v10
	global_store_dwordx2 v[14:15], v[8:9], off offset:32
	v_mul_f32_e32 v8, v5, v5
	v_mul_f32_e32 v9, v7, v7
	v_add_f32_e32 v18, v18, v19
	v_add_f32_e32 v12, v12, v13
	v_fmac_f32_e32 v8, v4, v4
	v_fmac_f32_e32 v9, v6, v6
	v_mul_f32_e32 v106, v53, v53
	v_mul_f32_e32 v107, v55, v55
	v_mul_f32_e32 v45, v43, v43
	v_mul_f32_e32 v29, v27, v27
	v_add_f32_e32 v12, v18, v12
	v_add_f32_e32 v8, v8, v9
	v_fmac_f32_e32 v106, v52, v52
	v_fmac_f32_e32 v107, v54, v54
	v_fmac_f32_e32 v45, v42, v42
	v_mul_f32_e32 v41, v39, v39
	v_fmac_f32_e32 v29, v26, v26
	v_mul_f32_e32 v25, v23, v23
	v_add_f32_e32 v12, v12, v8
	s_nop 0
	v_mov_b64_e32 v[10:11], v[2:3]
	v_mov_b64_e32 v[8:9], v[0:1]
	v_add_f32_e32 v49, v106, v107
	v_add_f32_e32 v44, v44, v45
	v_fmac_f32_e32 v41, v38, v38
	v_add_f32_e32 v34, v34, v35
	v_add_f32_e32 v28, v28, v29
	v_fmac_f32_e32 v25, v22, v22
	v_mul_f32_e32 v0, v9, v9
	v_mul_f32_e32 v1, v11, v11
	v_add_f32_e32 v44, v49, v44
	v_add_f32_e32 v40, v40, v41
	v_add_f32_e32 v28, v34, v28
	v_add_f32_e32 v24, v24, v25
	v_fmac_f32_e32 v0, v8, v8
	v_fmac_f32_e32 v1, v10, v10
	v_add_f32_e32 v40, v44, v40
	v_add_f32_e32 v36, v36, v37
	v_add_f32_e32 v24, v28, v24
	v_add_f32_e32 v20, v20, v21
	v_add_f32_e32 v0, v0, v1
	v_add_f32_e32 v36, v40, v36
	v_add_f32_e32 v20, v24, v20
	v_add_f32_e32 v3, v12, v0
	global_store_dwordx4 v[86:87], v[4:7], off offset:512
	ds_bpermute_b32 v0, v96, v48
	ds_bpermute_b32 v1, v96, v36
	v_cvt_pk_bf16_f32 v4, v4, v5
	v_cvt_pk_bf16_f32 v5, v6, v7
	ds_bpermute_b32 v2, v96, v20
	ds_bpermute_b32 v6, v96, v3
	global_store_dwordx2 v[14:15], v[4:5], off offset:256
	s_waitcnt lgkmcnt(3)
	v_add_f32_e32 v0, v48, v0
	s_waitcnt lgkmcnt(2)
	v_add_f32_e32 v1, v36, v1
	s_waitcnt lgkmcnt(1)
	v_add_f32_e32 v2, v20, v2
	s_waitcnt lgkmcnt(0)
	v_add_f32_e32 v4, v3, v6
	ds_bpermute_b32 v3, v97, v0
	ds_bpermute_b32 v5, v97, v1
	ds_bpermute_b32 v6, v97, v2
	ds_bpermute_b32 v7, v97, v4
	global_store_dwordx4 v[86:87], v[8:11], off offset:576
	s_nop 1
	v_cvt_pk_bf16_f32 v8, v8, v9
	v_cvt_pk_bf16_f32 v9, v10, v11
	global_store_dwordx2 v[14:15], v[8:9], off offset:288
	s_and_saveexec_b64 s[6:7], s[2:3]
	s_cbranch_execz .LBB0_1480
	s_waitcnt lgkmcnt(3)
	v_add_f32_e32 v0, v0, v3
	s_waitcnt lgkmcnt(0)
	v_add_f32_e32 v4, v4, v7
	v_add_f32_e32 v2, v2, v6
	v_add_f32_e32 v1, v1, v5
	global_atomic_add_f32 v[84:85], v0, off offset:512
	global_atomic_add_f32 v[84:85], v1, off offset:576
	global_atomic_add_f32 v[84:85], v2, off offset:640
	global_atomic_add_f32 v[84:85], v4, off offset:704

.LBB0_1945:
	s_ashr_i32 s21, s20, 31
	s_lshl_b64 s[22:23], s[20:21], 22
	s_add_u32 s22, s46, s22
	s_addc_u32 s23, s47, s23
	s_and_b64 s[34:35], s[2:3], exec
	s_cselect_b32 s21, s23, s39
	s_cselect_b32 s61, s22, s38
	s_ashr_i32 s19, s18, 31
	s_lshl_b64 s[34:35], s[18:19], 20
	s_add_u32 s34, s48, s34
	s_addc_u32 s35, s49, s35
	s_and_b64 s[42:43], s[2:3], exec
	s_cselect_b32 s19, s35, s41
	s_cselect_b32 s62, s34, s40
	s_add_u32 s38, s38, 0x200080
	s_addc_u32 s39, s39, 0
	s_add_u32 s63, s40, 0x100
	s_addc_u32 s64, s41, 0
	s_mov_b32 s65, -2
	s_waitcnt vmcnt(0)
	v_readlane_b32 s98, v248, 6
	v_readlane_b32 s99, v248, 7
	v_lshl_add_u32 v249, s36, 8, v156
	v_lshl_or_b32 v250, s37, 8, v158
	v_lshlrev_b32_e32 v249, 13, v249
	v_lshl_add_u32 v249, v250, 2, v249
	s_nop 1
	global_load_dwordx4 v[124:127], v249, s[98:99]
	global_load_dwordx4 v[120:123], v249, s[98:99] offset:64
	global_load_dwordx4 v[108:111], v249, s[98:99] offset:512
	global_load_dwordx4 v[100:103], v249, s[98:99] offset:576
	v_add_u32_e32 v249, 0x20000, v249
	global_load_dwordx4 v[116:119], v249, s[98:99]
	global_load_dwordx4 v[112:115], v249, s[98:99] offset:64
	global_load_dwordx4 v[92:95], v249, s[98:99] offset:512
	global_load_dwordx4 v[84:87], v249, s[98:99] offset:576
	v_add_u32_e32 v249, 0x20000, v249
	global_load_dwordx4 v[104:107], v249, s[98:99]
	global_load_dwordx4 v[96:99], v249, s[98:99] offset:64
	global_load_dwordx4 v[76:79], v249, s[98:99] offset:512
	global_load_dwordx4 v[72:75], v249, s[98:99] offset:576
	v_add_u32_e32 v249, 0x20000, v249
	global_load_dwordx4 v[88:91], v249, s[98:99]
	global_load_dwordx4 v[80:83], v249, s[98:99] offset:64
	global_load_dwordx4 v[68:71], v249, s[98:99] offset:512
	global_load_dwordx4 v[64:67], v249, s[98:99] offset:576
	v_add_u32_e32 v249, 0xa0000, v249
	global_load_dwordx4 v[60:63], v249, s[98:99]
	global_load_dwordx4 v[56:59], v249, s[98:99] offset:64
	global_load_dwordx4 v[48:51], v249, s[98:99] offset:512
	global_load_dwordx4 v[40:43], v249, s[98:99] offset:576
	v_add_u32_e32 v249, 0x20000, v249
	global_load_dwordx4 v[52:55], v249, s[98:99]
	global_load_dwordx4 v[44:47], v249, s[98:99] offset:64
	global_load_dwordx4 v[32:35], v249, s[98:99] offset:512
	global_load_dwordx4 v[24:27], v249, s[98:99] offset:576
	v_add_u32_e32 v249, 0x20000, v249
	global_load_dwordx4 v[36:39], v249, s[98:99]
	global_load_dwordx4 v[28:31], v249, s[98:99] offset:64
	global_load_dwordx4 v[16:19], v249, s[98:99] offset:512
	global_load_dwordx4 v[12:15], v249, s[98:99] offset:576
	v_add_u32_e32 v249, 0x20000, v249
	global_load_dwordx4 v[20:23], v249, s[98:99]
	global_load_dwordx4 v[8:11], v249, s[98:99] offset:64
	global_load_dwordx4 v[4:7], v249, s[98:99] offset:512
	global_load_dwordx4 v[0:3], v249, s[98:99] offset:576

.LBB0_1949:
	v_lshl_add_u32 v154, s36, 8, v156
	v_lshl_or_b32 v144, s37, 8, v158
	v_readlane_b32 s36, v248, 0
	v_readlane_b32 s40, v248, 4
	v_readlane_b32 s41, v248, 5
	v_ashrrev_i32_e32 v145, 31, v144
	v_readlane_b32 s42, v248, 6
	v_readlane_b32 s43, v248, 7
	s_mov_b64 s[24:25], s[40:41]
	v_lshlrev_b64 v[144:145], 2, v[144:145]
	s_mov_b64 s[26:27], s[42:43]
	v_ashrrev_i32_e32 v155, 31, v154
	v_lshl_add_u64 v[146:147], s[26:27], 0, v[144:145]
	v_lshlrev_b64 v[148:149], 13, v[154:155]
	v_or_b32_e32 v174, 16, v154
	v_lshl_add_u64 v[170:171], v[146:147], 0, v[148:149]
	v_ashrrev_i32_e32 v175, 31, v174
	s_nop 0
	s_nop 0
	s_nop 0
	s_nop 0
	s_nop 0
	v_lshlrev_b64 v[218:219], 13, v[174:175]
	v_or_b32_e32 v190, 32, v154
	v_lshl_add_u64 v[186:187], v[146:147], 0, v[218:219]
	v_ashrrev_i32_e32 v191, 31, v190
	s_nop 0
	s_nop 0
	s_nop 0
	s_nop 0
	s_nop 0
	v_lshlrev_b64 v[226:227], 13, v[190:191]
	v_or_b32_e32 v154, 48, v154
	v_lshl_add_u64 v[202:203], v[146:147], 0, v[226:227]
	v_ashrrev_i32_e32 v155, 31, v154
	s_nop 0
	s_nop 0
	s_nop 0
	s_nop 0
	s_nop 0
	v_lshlrev_b64 v[154:155], 13, v[154:155]
	v_lshl_add_u64 v[222:223], v[146:147], 0, v[154:155]
	s_nop 0
	s_nop 0
	s_nop 0
	s_nop 0
	s_nop 0
	v_readlane_b32 s37, v248, 1
	s_mov_b64 s[36:37], -1
	s_andn2_b64 vcc, exec, s[2:3]
	v_readlane_b32 s38, v248, 2
	v_readlane_b32 s39, v248, 3
	s_nop 0
	s_nop 0
	v_lshl_add_u64 v[150:151], s[26:27], 0, v[148:149]
	v_lshl_add_u64 v[150:151], v[150:151], 0, v[144:145]
	s_nop 0
	s_nop 0
	global_store_dwordx4 v[150:151], v[108:111], off offset:512
	s_nop 0
	s_nop 0
	v_lshl_add_u64 v[108:109], s[26:27], 0, v[218:219]
	v_lshl_add_u64 v[108:109], v[108:109], 0, v[144:145]
	s_nop 0
	global_store_dwordx4 v[108:109], v[92:95], off offset:512
	s_nop 0
	s_nop 0
	v_lshl_add_u64 v[92:93], s[26:27], 0, v[226:227]
	v_lshl_add_u64 v[92:93], v[92:93], 0, v[144:145]
	s_nop 0
	s_nop 0
	s_nop 0
	global_store_dwordx4 v[92:93], v[76:79], off offset:512
	s_nop 0
	s_nop 0
	v_lshl_add_u64 v[76:77], s[26:27], 0, v[154:155]
	global_store_dwordx4 v[150:151], v[100:103], off offset:576
	global_store_dwordx4 v[108:109], v[84:87], off offset:576
	global_store_dwordx4 v[92:93], v[72:75], off offset:576
	v_mov_b64_e32 v[102:103], v[118:119]
	v_mov_b64_e32 v[100:101], v[116:117]
	v_mov_b64_e32 v[86:87], v[106:107]
	v_mov_b64_e32 v[84:85], v[104:105]
	v_mov_b64_e32 v[74:75], v[90:91]
	v_mov_b64_e32 v[72:73], v[88:89]
	v_lshl_add_u64 v[76:77], v[76:77], 0, v[144:145]
	s_nop 0
	s_nop 0
	s_nop 0
	global_store_dwordx4 v[108:109], v[100:103], off
	global_store_dwordx4 v[92:93], v[84:87], off
	global_store_dwordx4 v[76:77], v[72:75], off
	v_mov_b64_e32 v[102:103], v[114:115]
	v_mov_b64_e32 v[100:101], v[112:113]
	v_mov_b64_e32 v[86:87], v[98:99]
	v_mov_b64_e32 v[84:85], v[96:97]
	v_mov_b64_e32 v[74:75], v[82:83]
	v_mov_b64_e32 v[72:73], v[80:81]
	s_nop 0
	s_nop 0
	s_nop 0
	s_nop 0
	v_lshl_add_u64 v[154:155], v[148:149], 0, s[10:11]
	global_store_dwordx4 v[150:151], v[124:127], off
	global_store_dwordx4 v[150:151], v[120:123], off offset:64
	global_store_dwordx4 v[108:109], v[100:103], off offset:64
	global_store_dwordx4 v[92:93], v[84:87], off offset:64
	global_store_dwordx4 v[76:77], v[72:75], off offset:64
	global_store_dwordx4 v[76:77], v[68:71], off offset:512
	global_store_dwordx4 v[76:77], v[64:67], off offset:576
	v_lshl_add_u64 v[152:153], v[148:149], 0, s[12:13]
	v_lshl_add_u64 v[150:151], v[148:149], 0, s[14:15]
	v_lshl_add_u64 v[64:65], v[146:147], 0, v[154:155]
	s_nop 0
	s_nop 0
	s_nop 0
	s_nop 0
	v_lshl_add_u64 v[64:65], v[146:147], 0, v[152:153]
	s_nop 0
	s_nop 0
	s_nop 0
	s_nop 0
	v_lshl_add_u64 v[64:65], v[146:147], 0, v[150:151]
	v_lshl_add_u64 v[148:149], v[148:149], 0, s[16:17]
	s_nop 0
	s_nop 0
	s_nop 0
	s_nop 0
	s_nop 0
	v_lshl_add_u64 v[124:125], v[146:147], 0, v[148:149]
	s_nop 0
	s_nop 0
	s_nop 0
	s_nop 0
	s_nop 0
	s_nop 0
	s_nop 0
	v_lshl_add_u64 v[116:117], s[26:27], 0, v[154:155]
	v_lshl_add_u64 v[116:117], v[116:117], 0, v[144:145]
	s_nop 0
	s_nop 0
	s_nop 0
	global_store_dwordx4 v[116:117], v[48:51], off offset:512
	s_nop 0
	s_nop 0
	s_nop 0
	v_lshl_add_u64 v[48:49], s[26:27], 0, v[152:153]
	v_lshl_add_u64 v[48:49], v[48:49], 0, v[144:145]
	global_store_dwordx4 v[48:49], v[32:35], off offset:512
	s_nop 0
	s_nop 0
	v_lshl_add_u64 v[32:33], s[26:27], 0, v[150:151]
	s_nop 0
	s_nop 0
	s_nop 0
	v_lshl_add_u64 v[32:33], v[32:33], 0, v[144:145]
	s_nop 0
	s_nop 0
	s_nop 0
	global_store_dwordx4 v[116:117], v[40:43], off offset:576
	global_store_dwordx4 v[48:49], v[24:27], off offset:576
	global_store_dwordx4 v[32:33], v[16:19], off offset:512
	v_mov_b64_e32 v[42:43], v[54:55]
	v_mov_b64_e32 v[40:41], v[52:53]
	v_mov_b64_e32 v[26:27], v[38:39]
	v_mov_b64_e32 v[24:25], v[36:37]
	s_nop 0
	s_nop 0
	s_nop 0
	v_lshl_add_u64 v[16:17], s[26:27], 0, v[148:149]
	s_nop 0
	s_nop 0
	s_nop 0
	global_store_dwordx4 v[48:49], v[40:43], off
	global_store_dwordx4 v[32:33], v[24:27], off
	global_store_dwordx4 v[32:33], v[12:15], off offset:576
	v_mov_b64_e32 v[42:43], v[46:47]
	v_mov_b64_e32 v[40:41], v[44:45]
	v_mov_b64_e32 v[26:27], v[30:31]
	v_mov_b64_e32 v[24:25], v[28:29]
	s_nop 0
	v_mov_b64_e32 v[14:15], v[22:23]
	v_mov_b64_e32 v[12:13], v[20:21]
	v_lshl_add_u64 v[16:17], v[16:17], 0, v[144:145]
	s_nop 0
	s_nop 0
	s_nop 0
	s_nop 0
	s_nop 0
	s_nop 0
	s_nop 0
	s_nop 0
	s_nop 0
	global_store_dwordx4 v[116:117], v[60:63], off
	global_store_dwordx4 v[116:117], v[56:59], off offset:64
	global_store_dwordx4 v[48:49], v[40:43], off offset:64
	global_store_dwordx4 v[32:33], v[24:27], off offset:64
	global_store_dwordx4 v[16:17], v[12:15], off
	global_store_dwordx4 v[16:17], v[8:11], off offset:64
	global_store_dwordx4 v[16:17], v[4:7], off offset:512
	global_store_dwordx4 v[16:17], v[0:3], off offset:576
	s_cbranch_vccnz .LBB0_1938
	s_andn2_b64 vcc, exec, s[4:5]
	s_cbranch_vccnz .LBB0_1937
	s_barrier
	s_branch .LBB0_1937
